# T7 + EpiUq epilogue: rms-norm rstd of the 31 later rows precomputed in a pre-pass (8 loads in flight) instead of 2 serialised loads + vmcnt(0) per store iteration
# speedup vs baseline: 1.0203x; 1.0072x over previous
; #define GAS __attribute__((address_space(1)))
; __device__ __forceinline__ float rstd_from_ssq(const float* __restrict__ ssq, int row) {
;     const f32x4 a = *(const GAS f32x4*)(ssq + (size_t)row * 8), c = *(const GAS f32x4*)(ssq + (size_t)row * 8 + 4);
;     return rsqrtf(((a[0] + a[1]) + (a[2] + a[3]) + (c[0] + c[1]) + (c[2] + c[3])) * (1.f / 512.f) + RMS_EPS);
; }
;     __device__ __forceinline__ void operator()(const f32x4 (&acc)[2][2][4][2], int brow, int bcol, int wr, int wc, int fr, int fq) const {
;     ...
;                 for (int j = 0; j < 4; ++j) {
;                     const int row = brow + ai * 128 + wr * 64 + m * 16 + fq * 4 + j, sq = row & 4095;
;                     const float rs = rstd_from_ssq(ssq, row);
.LBB0_751:
	s_or_b64 exec, exec, s[12:13]
	v_lshlrev_b32_e32 v1, 2, v1
	v_add_u32_e32 v133, s42, v133
	v_or_b32_e32 v134, v133, v1
	v_ashrrev_i32_e32 v135, 31, v134
	v_or_b32_e32 v240, 1, v134
	v_ashrrev_i32_e32 v241, 31, v240
	v_lshlrev_b64 v[240:241], 5, v[240:241]
	v_lshl_add_u64 v[240:241], s[46:47], 0, v[240:241]
	global_load_dwordx4 v[208:211], v[240:241], off offset:16
	global_load_dwordx4 v[224:227], v[240:241], off
	v_or_b32_e32 v240, 2, v134
	v_ashrrev_i32_e32 v241, 31, v240
	v_lshlrev_b64 v[240:241], 5, v[240:241]
	v_lshl_add_u64 v[240:241], s[46:47], 0, v[240:241]
	global_load_dwordx4 v[212:215], v[240:241], off offset:16
	global_load_dwordx4 v[228:231], v[240:241], off
	v_or_b32_e32 v240, 3, v134
	v_ashrrev_i32_e32 v241, 31, v240
	v_lshlrev_b64 v[240:241], 5, v[240:241]
	v_lshl_add_u64 v[240:241], s[46:47], 0, v[240:241]
	global_load_dwordx4 v[216:219], v[240:241], off offset:16
	global_load_dwordx4 v[232:235], v[240:241], off
	v_or_b32_e32 v240, 16, v134
	v_ashrrev_i32_e32 v241, 31, v240
	v_lshlrev_b64 v[240:241], 5, v[240:241]
	v_lshl_add_u64 v[240:241], s[46:47], 0, v[240:241]
	global_load_dwordx4 v[220:223], v[240:241], off offset:16
	global_load_dwordx4 v[236:239], v[240:241], off
	s_waitcnt vmcnt(6)
	v_add_f32_e32 v242, v225, v224
	v_add_f32_e32 v243, v226, v227
	v_add_f32_e32 v244, v210, v211
	v_add_f32_e32 v245, v208, v209
	v_add_f32_e32 v242, v242, v243
	v_add_f32_e32 v242, v242, v245
	v_add_f32_e32 v242, v244, v242
	v_fmamk_f32 v242, v242, 0x3b000000, v201
	v_cmp_gt_f32_e32 vcc, s33, v242
	v_mul_f32_e32 v243, 0x4b800000, v242
	s_nop 0
	v_cndmask_b32_e32 v242, v242, v243, vcc
	v_rsq_f32_e32 v242, v242
	s_nop 0
	v_mul_f32_e32 v243, 0x45800000, v242
	v_cndmask_b32_e32 v154, v242, v243, vcc
	s_waitcnt vmcnt(4)
	v_add_f32_e32 v242, v229, v228
	v_add_f32_e32 v243, v230, v231
	v_add_f32_e32 v244, v214, v215
	v_add_f32_e32 v245, v212, v213
	v_add_f32_e32 v242, v242, v243
	v_add_f32_e32 v242, v242, v245
	v_add_f32_e32 v242, v244, v242
	v_fmamk_f32 v242, v242, 0x3b000000, v201
	v_cmp_gt_f32_e32 vcc, s33, v242
	v_mul_f32_e32 v243, 0x4b800000, v242
	s_nop 0
	v_cndmask_b32_e32 v242, v242, v243, vcc
	v_rsq_f32_e32 v242, v242
	s_nop 0
	v_mul_f32_e32 v243, 0x45800000, v242
	v_cndmask_b32_e32 v155, v242, v243, vcc
	s_waitcnt vmcnt(2)
	v_add_f32_e32 v242, v233, v232
	v_add_f32_e32 v243, v234, v235
	v_add_f32_e32 v244, v218, v219
	v_add_f32_e32 v245, v216, v217
	v_add_f32_e32 v242, v242, v243
	v_add_f32_e32 v242, v242, v245
	v_add_f32_e32 v242, v244, v242
	v_fmamk_f32 v242, v242, 0x3b000000, v201
	v_cmp_gt_f32_e32 vcc, s33, v242
	v_mul_f32_e32 v243, 0x4b800000, v242
	s_nop 0
	v_cndmask_b32_e32 v242, v242, v243, vcc
	v_rsq_f32_e32 v242, v242
	s_nop 0
	v_mul_f32_e32 v243, 0x45800000, v242
	v_cndmask_b32_e32 v156, v242, v243, vcc
	s_waitcnt vmcnt(0)
	v_add_f32_e32 v242, v237, v236
	v_add_f32_e32 v243, v238, v239
	v_add_f32_e32 v244, v222, v223
	v_add_f32_e32 v245, v220, v221
	v_add_f32_e32 v242, v242, v243
	v_add_f32_e32 v242, v242, v245
	v_add_f32_e32 v242, v244, v242
	v_fmamk_f32 v242, v242, 0x3b000000, v201
	v_cmp_gt_f32_e32 vcc, s33, v242
	v_mul_f32_e32 v243, 0x4b800000, v242
	s_nop 0
	v_cndmask_b32_e32 v242, v242, v243, vcc
	v_rsq_f32_e32 v242, v242
	s_nop 0
	v_mul_f32_e32 v243, 0x45800000, v242
	v_cndmask_b32_e32 v157, v242, v243, vcc
	v_or_b32_e32 v240, 17, v134
	v_ashrrev_i32_e32 v241, 31, v240
	v_lshlrev_b64 v[240:241], 5, v[240:241]
	v_lshl_add_u64 v[240:241], s[46:47], 0, v[240:241]
	global_load_dwordx4 v[208:211], v[240:241], off offset:16
	global_load_dwordx4 v[224:227], v[240:241], off
	v_or_b32_e32 v240, 18, v134
	v_ashrrev_i32_e32 v241, 31, v240
	v_lshlrev_b64 v[240:241], 5, v[240:241]
	v_lshl_add_u64 v[240:241], s[46:47], 0, v[240:241]
	global_load_dwordx4 v[212:215], v[240:241], off offset:16
	global_load_dwordx4 v[228:231], v[240:241], off
	v_or_b32_e32 v240, 19, v134
	v_ashrrev_i32_e32 v241, 31, v240
	v_lshlrev_b64 v[240:241], 5, v[240:241]
	v_lshl_add_u64 v[240:241], s[46:47], 0, v[240:241]
	global_load_dwordx4 v[216:219], v[240:241], off offset:16
	global_load_dwordx4 v[232:235], v[240:241], off
	v_or_b32_e32 v240, 32, v134
	v_ashrrev_i32_e32 v241, 31, v240
	v_lshlrev_b64 v[240:241], 5, v[240:241]
	v_lshl_add_u64 v[240:241], s[46:47], 0, v[240:241]
	global_load_dwordx4 v[220:223], v[240:241], off offset:16
	global_load_dwordx4 v[236:239], v[240:241], off
	s_waitcnt vmcnt(6)
	v_add_f32_e32 v242, v225, v224
	v_add_f32_e32 v243, v226, v227
	v_add_f32_e32 v244, v210, v211
	v_add_f32_e32 v245, v208, v209
	v_add_f32_e32 v242, v242, v243
	v_add_f32_e32 v242, v242, v245
	v_add_f32_e32 v242, v244, v242
	v_fmamk_f32 v242, v242, 0x3b000000, v201
	v_cmp_gt_f32_e32 vcc, s33, v242
	v_mul_f32_e32 v243, 0x4b800000, v242
	s_nop 0
	v_cndmask_b32_e32 v242, v242, v243, vcc
	v_rsq_f32_e32 v242, v242
	s_nop 0
	v_mul_f32_e32 v243, 0x45800000, v242
	v_cndmask_b32_e32 v158, v242, v243, vcc
	s_waitcnt vmcnt(4)
	v_add_f32_e32 v242, v229, v228
	v_add_f32_e32 v243, v230, v231
	v_add_f32_e32 v244, v214, v215
	v_add_f32_e32 v245, v212, v213
	v_add_f32_e32 v242, v242, v243
	v_add_f32_e32 v242, v242, v245
	v_add_f32_e32 v242, v244, v242
	v_fmamk_f32 v242, v242, 0x3b000000, v201
	v_cmp_gt_f32_e32 vcc, s33, v242
	v_mul_f32_e32 v243, 0x4b800000, v242
	s_nop 0
	v_cndmask_b32_e32 v242, v242, v243, vcc
	v_rsq_f32_e32 v242, v242
	s_nop 0
	v_mul_f32_e32 v243, 0x45800000, v242
	v_cndmask_b32_e32 v159, v242, v243, vcc
	s_waitcnt vmcnt(2)
; #define GAS __attribute__((address_space(1)))
; __device__ __forceinline__ float rstd_from_ssq(const float* __restrict__ ssq, int row) {
;     const f32x4 a = *(const GAS f32x4*)(ssq + (size_t)row * 8), c = *(const GAS f32x4*)(ssq + (size_t)row * 8 + 4);
;     return rsqrtf(((a[0] + a[1]) + (a[2] + a[3]) + (c[0] + c[1]) + (c[2] + c[3])) * (1.f / 512.f) + RMS_EPS);
; }
;     __device__ __forceinline__ void operator()(const f32x4 (&acc)[2][2][4][2], int brow, int bcol, int wr, int wc, int fr, int fq) const {
;     ...
;                     const int row = brow + ai * 128 + wr * 64 + m * 16 + fq * 4 + j, sq = row & 4095;
;                     const float rs = rstd_from_ssq(ssq, row);
	v_add_f32_e32 v242, v233, v232
	v_add_f32_e32 v243, v234, v235
	v_add_f32_e32 v244, v218, v219
	v_add_f32_e32 v245, v216, v217
	v_add_f32_e32 v242, v242, v243
	v_add_f32_e32 v242, v242, v245
	v_add_f32_e32 v242, v244, v242
	v_fmamk_f32 v242, v242, 0x3b000000, v201
	v_cmp_gt_f32_e32 vcc, s33, v242
	v_mul_f32_e32 v243, 0x4b800000, v242
	s_nop 0
	v_cndmask_b32_e32 v242, v242, v243, vcc
	v_rsq_f32_e32 v242, v242
	s_nop 0
	v_mul_f32_e32 v243, 0x45800000, v242
	v_cndmask_b32_e32 v160, v242, v243, vcc
	s_waitcnt vmcnt(0)
	v_add_f32_e32 v242, v237, v236
	v_add_f32_e32 v243, v238, v239
	v_add_f32_e32 v244, v222, v223
	v_add_f32_e32 v245, v220, v221
	v_add_f32_e32 v242, v242, v243
	v_add_f32_e32 v242, v242, v245
	v_add_f32_e32 v242, v244, v242
	v_fmamk_f32 v242, v242, 0x3b000000, v201
	v_cmp_gt_f32_e32 vcc, s33, v242
	v_mul_f32_e32 v243, 0x4b800000, v242
	s_nop 0
	v_cndmask_b32_e32 v242, v242, v243, vcc
	v_rsq_f32_e32 v242, v242
	s_nop 0
	v_mul_f32_e32 v243, 0x45800000, v242
	v_cndmask_b32_e32 v161, v242, v243, vcc
	v_or_b32_e32 v240, 33, v134
	v_ashrrev_i32_e32 v241, 31, v240
	v_lshlrev_b64 v[240:241], 5, v[240:241]
	v_lshl_add_u64 v[240:241], s[46:47], 0, v[240:241]
	global_load_dwordx4 v[208:211], v[240:241], off offset:16
	global_load_dwordx4 v[224:227], v[240:241], off
	v_or_b32_e32 v240, 34, v134
	v_ashrrev_i32_e32 v241, 31, v240
	v_lshlrev_b64 v[240:241], 5, v[240:241]
	v_lshl_add_u64 v[240:241], s[46:47], 0, v[240:241]
	global_load_dwordx4 v[212:215], v[240:241], off offset:16
	global_load_dwordx4 v[228:231], v[240:241], off
	v_or_b32_e32 v240, 35, v134
	v_ashrrev_i32_e32 v241, 31, v240
	v_lshlrev_b64 v[240:241], 5, v[240:241]
	v_lshl_add_u64 v[240:241], s[46:47], 0, v[240:241]
	global_load_dwordx4 v[216:219], v[240:241], off offset:16
	global_load_dwordx4 v[232:235], v[240:241], off
	v_or_b32_e32 v240, 48, v134
	v_ashrrev_i32_e32 v241, 31, v240
	v_lshlrev_b64 v[240:241], 5, v[240:241]
	v_lshl_add_u64 v[240:241], s[46:47], 0, v[240:241]
	global_load_dwordx4 v[220:223], v[240:241], off offset:16
	global_load_dwordx4 v[236:239], v[240:241], off
	s_waitcnt vmcnt(6)
	v_add_f32_e32 v242, v225, v224
	v_add_f32_e32 v243, v226, v227
	v_add_f32_e32 v244, v210, v211
	v_add_f32_e32 v245, v208, v209
	v_add_f32_e32 v242, v242, v243
	v_add_f32_e32 v242, v242, v245
	v_add_f32_e32 v242, v244, v242
	v_fmamk_f32 v242, v242, 0x3b000000, v201
	v_cmp_gt_f32_e32 vcc, s33, v242
	v_mul_f32_e32 v243, 0x4b800000, v242
	s_nop 0
	v_cndmask_b32_e32 v242, v242, v243, vcc
	v_rsq_f32_e32 v242, v242
	s_nop 0
	v_mul_f32_e32 v243, 0x45800000, v242
	v_cndmask_b32_e32 v162, v242, v243, vcc
	s_waitcnt vmcnt(4)
	v_add_f32_e32 v242, v229, v228
	v_add_f32_e32 v243, v230, v231
	v_add_f32_e32 v244, v214, v215
	v_add_f32_e32 v245, v212, v213
	v_add_f32_e32 v242, v242, v243
	v_add_f32_e32 v242, v242, v245
	v_add_f32_e32 v242, v244, v242
	v_fmamk_f32 v242, v242, 0x3b000000, v201
	v_cmp_gt_f32_e32 vcc, s33, v242
	v_mul_f32_e32 v243, 0x4b800000, v242
	s_nop 0
	v_cndmask_b32_e32 v242, v242, v243, vcc
	v_rsq_f32_e32 v242, v242
	s_nop 0
	v_mul_f32_e32 v243, 0x45800000, v242
	v_cndmask_b32_e32 v163, v242, v243, vcc
	s_waitcnt vmcnt(2)
	v_add_f32_e32 v242, v233, v232
	v_add_f32_e32 v243, v234, v235
	v_add_f32_e32 v244, v218, v219
	v_add_f32_e32 v245, v216, v217
	v_add_f32_e32 v242, v242, v243
	v_add_f32_e32 v242, v242, v245
	v_add_f32_e32 v242, v244, v242
	v_fmamk_f32 v242, v242, 0x3b000000, v201
	v_cmp_gt_f32_e32 vcc, s33, v242
	v_mul_f32_e32 v243, 0x4b800000, v242
	s_nop 0
	v_cndmask_b32_e32 v242, v242, v243, vcc
	v_rsq_f32_e32 v242, v242
	s_nop 0
	v_mul_f32_e32 v243, 0x45800000, v242
	v_cndmask_b32_e32 v164, v242, v243, vcc
	s_waitcnt vmcnt(0)
	v_add_f32_e32 v242, v237, v236
	v_add_f32_e32 v243, v238, v239
	v_add_f32_e32 v244, v222, v223
	v_add_f32_e32 v245, v220, v221
	v_add_f32_e32 v242, v242, v243
	v_add_f32_e32 v242, v242, v245
	v_add_f32_e32 v242, v244, v242
	v_fmamk_f32 v242, v242, 0x3b000000, v201
	v_cmp_gt_f32_e32 vcc, s33, v242
	v_mul_f32_e32 v243, 0x4b800000, v242
	s_nop 0
	v_cndmask_b32_e32 v242, v242, v243, vcc
	v_rsq_f32_e32 v242, v242
	s_nop 0
	v_mul_f32_e32 v243, 0x45800000, v242
	v_cndmask_b32_e32 v165, v242, v243, vcc
	v_or_b32_e32 v240, 49, v134
	v_ashrrev_i32_e32 v241, 31, v240
	v_lshlrev_b64 v[240:241], 5, v[240:241]
	v_lshl_add_u64 v[240:241], s[46:47], 0, v[240:241]
	global_load_dwordx4 v[208:211], v[240:241], off offset:16
	global_load_dwordx4 v[224:227], v[240:241], off
	v_or_b32_e32 v240, 50, v134
	v_ashrrev_i32_e32 v241, 31, v240
	v_lshlrev_b64 v[240:241], 5, v[240:241]
	v_lshl_add_u64 v[240:241], s[46:47], 0, v[240:241]
	global_load_dwordx4 v[212:215], v[240:241], off offset:16
	global_load_dwordx4 v[228:231], v[240:241], off
	v_or_b32_e32 v240, 51, v134
	v_ashrrev_i32_e32 v241, 31, v240
	v_lshlrev_b64 v[240:241], 5, v[240:241]
	v_lshl_add_u64 v[240:241], s[46:47], 0, v[240:241]
	global_load_dwordx4 v[216:219], v[240:241], off offset:16
	global_load_dwordx4 v[232:235], v[240:241], off
	v_add_u32_e32 v240, 0x80, v134
	v_ashrrev_i32_e32 v241, 31, v240
	v_lshlrev_b64 v[240:241], 5, v[240:241]
	v_lshl_add_u64 v[240:241], s[46:47], 0, v[240:241]
	global_load_dwordx4 v[220:223], v[240:241], off offset:16
	global_load_dwordx4 v[236:239], v[240:241], off
	s_waitcnt vmcnt(6)
	v_add_f32_e32 v242, v225, v224
	v_add_f32_e32 v243, v226, v227
	v_add_f32_e32 v244, v210, v211
	v_add_f32_e32 v245, v208, v209
	v_add_f32_e32 v242, v242, v243
	v_add_f32_e32 v242, v242, v245
	v_add_f32_e32 v242, v244, v242
	v_fmamk_f32 v242, v242, 0x3b000000, v201
	v_cmp_gt_f32_e32 vcc, s33, v242
	v_mul_f32_e32 v243, 0x4b800000, v242
	s_nop 0
	v_cndmask_b32_e32 v242, v242, v243, vcc
	v_rsq_f32_e32 v242, v242
	s_nop 0
	v_mul_f32_e32 v243, 0x45800000, v242
	v_cndmask_b32_e32 v166, v242, v243, vcc
	s_waitcnt vmcnt(4)
; #define GAS __attribute__((address_space(1)))
; __device__ __forceinline__ float rstd_from_ssq(const float* __restrict__ ssq, int row) {
;     const f32x4 a = *(const GAS f32x4*)(ssq + (size_t)row * 8), c = *(const GAS f32x4*)(ssq + (size_t)row * 8 + 4);
;     return rsqrtf(((a[0] + a[1]) + (a[2] + a[3]) + (c[0] + c[1]) + (c[2] + c[3])) * (1.f / 512.f) + RMS_EPS);
; }
;     __device__ __forceinline__ void operator()(const f32x4 (&acc)[2][2][4][2], int brow, int bcol, int wr, int wc, int fr, int fq) const {
;     ...
;                     const int row = brow + ai * 128 + wr * 64 + m * 16 + fq * 4 + j, sq = row & 4095;
;                     const float rs = rstd_from_ssq(ssq, row);
	v_add_f32_e32 v242, v229, v228
	v_add_f32_e32 v243, v230, v231
	v_add_f32_e32 v244, v214, v215
	v_add_f32_e32 v245, v212, v213
	v_add_f32_e32 v242, v242, v243
	v_add_f32_e32 v242, v242, v245
	v_add_f32_e32 v242, v244, v242
	v_fmamk_f32 v242, v242, 0x3b000000, v201
	v_cmp_gt_f32_e32 vcc, s33, v242
	v_mul_f32_e32 v243, 0x4b800000, v242
	s_nop 0
	v_cndmask_b32_e32 v242, v242, v243, vcc
	v_rsq_f32_e32 v242, v242
	s_nop 0
	v_mul_f32_e32 v243, 0x45800000, v242
	v_cndmask_b32_e32 v167, v242, v243, vcc
	s_waitcnt vmcnt(2)
	v_add_f32_e32 v242, v233, v232
	v_add_f32_e32 v243, v234, v235
	v_add_f32_e32 v244, v218, v219
	v_add_f32_e32 v245, v216, v217
	v_add_f32_e32 v242, v242, v243
	v_add_f32_e32 v242, v242, v245
	v_add_f32_e32 v242, v244, v242
	v_fmamk_f32 v242, v242, 0x3b000000, v201
	v_cmp_gt_f32_e32 vcc, s33, v242
	v_mul_f32_e32 v243, 0x4b800000, v242
	s_nop 0
	v_cndmask_b32_e32 v242, v242, v243, vcc
	v_rsq_f32_e32 v242, v242
	s_nop 0
	v_mul_f32_e32 v243, 0x45800000, v242
	v_cndmask_b32_e32 v168, v242, v243, vcc
	s_waitcnt vmcnt(0)
	v_add_f32_e32 v242, v237, v236
	v_add_f32_e32 v243, v238, v239
	v_add_f32_e32 v244, v222, v223
	v_add_f32_e32 v245, v220, v221
	v_add_f32_e32 v242, v242, v243
	v_add_f32_e32 v242, v242, v245
	v_add_f32_e32 v242, v244, v242
	v_fmamk_f32 v242, v242, 0x3b000000, v201
	v_cmp_gt_f32_e32 vcc, s33, v242
	v_mul_f32_e32 v243, 0x4b800000, v242
	s_nop 0
	v_cndmask_b32_e32 v242, v242, v243, vcc
	v_rsq_f32_e32 v242, v242
	s_nop 0
	v_mul_f32_e32 v243, 0x45800000, v242
	v_cndmask_b32_e32 v169, v242, v243, vcc
	v_add_u32_e32 v240, 0x81, v134
	v_ashrrev_i32_e32 v241, 31, v240
	v_lshlrev_b64 v[240:241], 5, v[240:241]
	v_lshl_add_u64 v[240:241], s[46:47], 0, v[240:241]
	global_load_dwordx4 v[208:211], v[240:241], off offset:16
	global_load_dwordx4 v[224:227], v[240:241], off
	v_add_u32_e32 v240, 0x82, v134
	v_ashrrev_i32_e32 v241, 31, v240
	v_lshlrev_b64 v[240:241], 5, v[240:241]
	v_lshl_add_u64 v[240:241], s[46:47], 0, v[240:241]
	global_load_dwordx4 v[212:215], v[240:241], off offset:16
	global_load_dwordx4 v[228:231], v[240:241], off
	v_add_u32_e32 v240, 0x83, v134
	v_ashrrev_i32_e32 v241, 31, v240
	v_lshlrev_b64 v[240:241], 5, v[240:241]
	v_lshl_add_u64 v[240:241], s[46:47], 0, v[240:241]
	global_load_dwordx4 v[216:219], v[240:241], off offset:16
	global_load_dwordx4 v[232:235], v[240:241], off
	v_add_u32_e32 v240, 0x90, v134
	v_ashrrev_i32_e32 v241, 31, v240
	v_lshlrev_b64 v[240:241], 5, v[240:241]
	v_lshl_add_u64 v[240:241], s[46:47], 0, v[240:241]
	global_load_dwordx4 v[220:223], v[240:241], off offset:16
	global_load_dwordx4 v[236:239], v[240:241], off
	s_waitcnt vmcnt(6)
	v_add_f32_e32 v242, v225, v224
	v_add_f32_e32 v243, v226, v227
	v_add_f32_e32 v244, v210, v211
	v_add_f32_e32 v245, v208, v209
	v_add_f32_e32 v242, v242, v243
	v_add_f32_e32 v242, v242, v245
	v_add_f32_e32 v242, v244, v242
	v_fmamk_f32 v242, v242, 0x3b000000, v201
	v_cmp_gt_f32_e32 vcc, s33, v242
	v_mul_f32_e32 v243, 0x4b800000, v242
	s_nop 0
	v_cndmask_b32_e32 v242, v242, v243, vcc
	v_rsq_f32_e32 v242, v242
	s_nop 0
	v_mul_f32_e32 v243, 0x45800000, v242
	v_cndmask_b32_e32 v170, v242, v243, vcc
	s_waitcnt vmcnt(4)
	v_add_f32_e32 v242, v229, v228
	v_add_f32_e32 v243, v230, v231
	v_add_f32_e32 v244, v214, v215
	v_add_f32_e32 v245, v212, v213
	v_add_f32_e32 v242, v242, v243
	v_add_f32_e32 v242, v242, v245
	v_add_f32_e32 v242, v244, v242
	v_fmamk_f32 v242, v242, 0x3b000000, v201
	v_cmp_gt_f32_e32 vcc, s33, v242
	v_mul_f32_e32 v243, 0x4b800000, v242
	s_nop 0
	v_cndmask_b32_e32 v242, v242, v243, vcc
	v_rsq_f32_e32 v242, v242
	s_nop 0
	v_mul_f32_e32 v243, 0x45800000, v242
	v_cndmask_b32_e32 v171, v242, v243, vcc
	s_waitcnt vmcnt(2)
	v_add_f32_e32 v242, v233, v232
	v_add_f32_e32 v243, v234, v235
	v_add_f32_e32 v244, v218, v219
	v_add_f32_e32 v245, v216, v217
	v_add_f32_e32 v242, v242, v243
	v_add_f32_e32 v242, v242, v245
	v_add_f32_e32 v242, v244, v242
	v_fmamk_f32 v242, v242, 0x3b000000, v201
	v_cmp_gt_f32_e32 vcc, s33, v242
	v_mul_f32_e32 v243, 0x4b800000, v242
	s_nop 0
	v_cndmask_b32_e32 v242, v242, v243, vcc
	v_rsq_f32_e32 v242, v242
	s_nop 0
	v_mul_f32_e32 v243, 0x45800000, v242
	v_cndmask_b32_e32 v172, v242, v243, vcc
	s_waitcnt vmcnt(0)
	v_add_f32_e32 v242, v237, v236
	v_add_f32_e32 v243, v238, v239
	v_add_f32_e32 v244, v222, v223
	v_add_f32_e32 v245, v220, v221
	v_add_f32_e32 v242, v242, v243
	v_add_f32_e32 v242, v242, v245
	v_add_f32_e32 v242, v244, v242
	v_fmamk_f32 v242, v242, 0x3b000000, v201
	v_cmp_gt_f32_e32 vcc, s33, v242
	v_mul_f32_e32 v243, 0x4b800000, v242
	s_nop 0
	v_cndmask_b32_e32 v242, v242, v243, vcc
	v_rsq_f32_e32 v242, v242
	s_nop 0
	v_mul_f32_e32 v243, 0x45800000, v242
	v_cndmask_b32_e32 v173, v242, v243, vcc
	v_add_u32_e32 v240, 0x91, v134
	v_ashrrev_i32_e32 v241, 31, v240
	v_lshlrev_b64 v[240:241], 5, v[240:241]
	v_lshl_add_u64 v[240:241], s[46:47], 0, v[240:241]
	global_load_dwordx4 v[208:211], v[240:241], off offset:16
	global_load_dwordx4 v[224:227], v[240:241], off
	v_add_u32_e32 v240, 0x92, v134
	v_ashrrev_i32_e32 v241, 31, v240
	v_lshlrev_b64 v[240:241], 5, v[240:241]
	v_lshl_add_u64 v[240:241], s[46:47], 0, v[240:241]
	global_load_dwordx4 v[212:215], v[240:241], off offset:16
	global_load_dwordx4 v[228:231], v[240:241], off
	v_add_u32_e32 v240, 0x93, v134
	v_ashrrev_i32_e32 v241, 31, v240
	v_lshlrev_b64 v[240:241], 5, v[240:241]
	v_lshl_add_u64 v[240:241], s[46:47], 0, v[240:241]
	global_load_dwordx4 v[216:219], v[240:241], off offset:16
	global_load_dwordx4 v[232:235], v[240:241], off
	v_add_u32_e32 v240, 0xa0, v134
	v_ashrrev_i32_e32 v241, 31, v240
	v_lshlrev_b64 v[240:241], 5, v[240:241]
	v_lshl_add_u64 v[240:241], s[46:47], 0, v[240:241]
	global_load_dwordx4 v[220:223], v[240:241], off offset:16
	global_load_dwordx4 v[236:239], v[240:241], off
	s_waitcnt vmcnt(6)
; #define GAS __attribute__((address_space(1)))
; __device__ __forceinline__ float rstd_from_ssq(const float* __restrict__ ssq, int row) {
;     const f32x4 a = *(const GAS f32x4*)(ssq + (size_t)row * 8), c = *(const GAS f32x4*)(ssq + (size_t)row * 8 + 4);
;     return rsqrtf(((a[0] + a[1]) + (a[2] + a[3]) + (c[0] + c[1]) + (c[2] + c[3])) * (1.f / 512.f) + RMS_EPS);
; }
;     __device__ __forceinline__ void operator()(const f32x4 (&acc)[2][2][4][2], int brow, int bcol, int wr, int wc, int fr, int fq) const {
;     ...
;                     const int row = brow + ai * 128 + wr * 64 + m * 16 + fq * 4 + j, sq = row & 4095;
;                     const float rs = rstd_from_ssq(ssq, row);
	v_add_f32_e32 v242, v225, v224
	v_add_f32_e32 v243, v226, v227
	v_add_f32_e32 v244, v210, v211
	v_add_f32_e32 v245, v208, v209
	v_add_f32_e32 v242, v242, v243
	v_add_f32_e32 v242, v242, v245
	v_add_f32_e32 v242, v244, v242
	v_fmamk_f32 v242, v242, 0x3b000000, v201
	v_cmp_gt_f32_e32 vcc, s33, v242
	v_mul_f32_e32 v243, 0x4b800000, v242
	s_nop 0
	v_cndmask_b32_e32 v242, v242, v243, vcc
	v_rsq_f32_e32 v242, v242
	s_nop 0
	v_mul_f32_e32 v243, 0x45800000, v242
	v_cndmask_b32_e32 v174, v242, v243, vcc
	s_waitcnt vmcnt(4)
	v_add_f32_e32 v242, v229, v228
	v_add_f32_e32 v243, v230, v231
	v_add_f32_e32 v244, v214, v215
	v_add_f32_e32 v245, v212, v213
	v_add_f32_e32 v242, v242, v243
	v_add_f32_e32 v242, v242, v245
	v_add_f32_e32 v242, v244, v242
	v_fmamk_f32 v242, v242, 0x3b000000, v201
	v_cmp_gt_f32_e32 vcc, s33, v242
	v_mul_f32_e32 v243, 0x4b800000, v242
	s_nop 0
	v_cndmask_b32_e32 v242, v242, v243, vcc
	v_rsq_f32_e32 v242, v242
	s_nop 0
	v_mul_f32_e32 v243, 0x45800000, v242
	v_cndmask_b32_e32 v175, v242, v243, vcc
	s_waitcnt vmcnt(2)
	v_add_f32_e32 v242, v233, v232
	v_add_f32_e32 v243, v234, v235
	v_add_f32_e32 v244, v218, v219
	v_add_f32_e32 v245, v216, v217
	v_add_f32_e32 v242, v242, v243
	v_add_f32_e32 v242, v242, v245
	v_add_f32_e32 v242, v244, v242
	v_fmamk_f32 v242, v242, 0x3b000000, v201
	v_cmp_gt_f32_e32 vcc, s33, v242
	v_mul_f32_e32 v243, 0x4b800000, v242
	s_nop 0
	v_cndmask_b32_e32 v242, v242, v243, vcc
	v_rsq_f32_e32 v242, v242
	s_nop 0
	v_mul_f32_e32 v243, 0x45800000, v242
	v_cndmask_b32_e32 v176, v242, v243, vcc
	s_waitcnt vmcnt(0)
	v_add_f32_e32 v242, v237, v236
	v_add_f32_e32 v243, v238, v239
	v_add_f32_e32 v244, v222, v223
	v_add_f32_e32 v245, v220, v221
	v_add_f32_e32 v242, v242, v243
	v_add_f32_e32 v242, v242, v245
	v_add_f32_e32 v242, v244, v242
	v_fmamk_f32 v242, v242, 0x3b000000, v201
	v_cmp_gt_f32_e32 vcc, s33, v242
	v_mul_f32_e32 v243, 0x4b800000, v242
	s_nop 0
	v_cndmask_b32_e32 v242, v242, v243, vcc
	v_rsq_f32_e32 v242, v242
	s_nop 0
	v_mul_f32_e32 v243, 0x45800000, v242
	v_cndmask_b32_e32 v177, v242, v243, vcc
	v_add_u32_e32 v240, 0xa1, v134
	v_ashrrev_i32_e32 v241, 31, v240
	v_lshlrev_b64 v[240:241], 5, v[240:241]
	v_lshl_add_u64 v[240:241], s[46:47], 0, v[240:241]
	global_load_dwordx4 v[208:211], v[240:241], off offset:16
	global_load_dwordx4 v[224:227], v[240:241], off
	v_add_u32_e32 v240, 0xa2, v134
	v_ashrrev_i32_e32 v241, 31, v240
	v_lshlrev_b64 v[240:241], 5, v[240:241]
	v_lshl_add_u64 v[240:241], s[46:47], 0, v[240:241]
	global_load_dwordx4 v[212:215], v[240:241], off offset:16
	global_load_dwordx4 v[228:231], v[240:241], off
	v_add_u32_e32 v240, 0xa3, v134
	v_ashrrev_i32_e32 v241, 31, v240
	v_lshlrev_b64 v[240:241], 5, v[240:241]
	v_lshl_add_u64 v[240:241], s[46:47], 0, v[240:241]
	global_load_dwordx4 v[216:219], v[240:241], off offset:16
	global_load_dwordx4 v[232:235], v[240:241], off
	v_add_u32_e32 v240, 0xb0, v134
	v_ashrrev_i32_e32 v241, 31, v240
	v_lshlrev_b64 v[240:241], 5, v[240:241]
	v_lshl_add_u64 v[240:241], s[46:47], 0, v[240:241]
	global_load_dwordx4 v[220:223], v[240:241], off offset:16
	global_load_dwordx4 v[236:239], v[240:241], off
	s_waitcnt vmcnt(6)
	v_add_f32_e32 v242, v225, v224
	v_add_f32_e32 v243, v226, v227
	v_add_f32_e32 v244, v210, v211
	v_add_f32_e32 v245, v208, v209
	v_add_f32_e32 v242, v242, v243
	v_add_f32_e32 v242, v242, v245
	v_add_f32_e32 v242, v244, v242
	v_fmamk_f32 v242, v242, 0x3b000000, v201
	v_cmp_gt_f32_e32 vcc, s33, v242
	v_mul_f32_e32 v243, 0x4b800000, v242
	s_nop 0
	v_cndmask_b32_e32 v242, v242, v243, vcc
	v_rsq_f32_e32 v242, v242
	s_nop 0
	v_mul_f32_e32 v243, 0x45800000, v242
	v_cndmask_b32_e32 v178, v242, v243, vcc
	s_waitcnt vmcnt(4)
	v_add_f32_e32 v242, v229, v228
	v_add_f32_e32 v243, v230, v231
	v_add_f32_e32 v244, v214, v215
	v_add_f32_e32 v245, v212, v213
	v_add_f32_e32 v242, v242, v243
	v_add_f32_e32 v242, v242, v245
	v_add_f32_e32 v242, v244, v242
	v_fmamk_f32 v242, v242, 0x3b000000, v201
	v_cmp_gt_f32_e32 vcc, s33, v242
	v_mul_f32_e32 v243, 0x4b800000, v242
	s_nop 0
	v_cndmask_b32_e32 v242, v242, v243, vcc
	v_rsq_f32_e32 v242, v242
	s_nop 0
	v_mul_f32_e32 v243, 0x45800000, v242
	v_cndmask_b32_e32 v179, v242, v243, vcc
	s_waitcnt vmcnt(2)
	v_add_f32_e32 v242, v233, v232
	v_add_f32_e32 v243, v234, v235
	v_add_f32_e32 v244, v218, v219
	v_add_f32_e32 v245, v216, v217
	v_add_f32_e32 v242, v242, v243
	v_add_f32_e32 v242, v242, v245
	v_add_f32_e32 v242, v244, v242
	v_fmamk_f32 v242, v242, 0x3b000000, v201
	v_cmp_gt_f32_e32 vcc, s33, v242
	v_mul_f32_e32 v243, 0x4b800000, v242
	s_nop 0
	v_cndmask_b32_e32 v242, v242, v243, vcc
	v_rsq_f32_e32 v242, v242
	s_nop 0
	v_mul_f32_e32 v243, 0x45800000, v242
	v_cndmask_b32_e32 v180, v242, v243, vcc
	s_waitcnt vmcnt(0)
; #define GAS __attribute__((address_space(1)))
; __device__ __forceinline__ unsigned cvtpk(float lo, float hi) { return __builtin_bit_cast(unsigned, __builtin_convertvector(f32x2_cv{lo, hi}, bf16x2_cv)); }
; __device__ __forceinline__ bf16_t f2bf(float f) { return (bf16_t)(cvtpk(f, 0.f) & 0xffffu); }
; __device__ __forceinline__ float rstd_from_ssq(const float* __restrict__ ssq, int row) {
;     const f32x4 a = *(const GAS f32x4*)(ssq + (size_t)row * 8), c = *(const GAS f32x4*)(ssq + (size_t)row * 8 + 4);
;     return rsqrtf(((a[0] + a[1]) + (a[2] + a[3]) + (c[0] + c[1]) + (c[2] + c[3])) * (1.f / 512.f) + RMS_EPS);
; }
;     __device__ __forceinline__ void operator()(const f32x4 (&acc)[2][2][4][2], int brow, int bcol, int wr, int wc, int fr, int fq) const {
;     ...
;                     const int row = brow + ai * 128 + wr * 64 + m * 16 + fq * 4 + j, sq = row & 4095;
;                     const float rs = rstd_from_ssq(ssq, row);
;                     if (bcol < 1024) {
; #pragma unroll
;                         for (int bj = 0; bj < 2; ++bj)
;                             *(GAS unsigned*)(qm + ((size_t)(b * 8 + (bcol >> 7) + bj) * S + sq) * 192 + wc * 32 + 2 * fr) = cvtpk(acc[ai][bj][m][0][j] * rs, acc[ai][bj][m][1][j] * rs);
;                     } else {
;                         const int i = (wc & 1) * 16 + fr;
;                         const float2 cs = r64[sq * 32 + i];
; #pragma unroll
;                         for (int bj = 0; bj < 2; ++bj) {
;                             const int head = ((bcol - 1024) >> 8) * 4 + bj * 2 + (wc >> 1);
;                             const float x1 = acc[ai][bj][m][0][j] * rs, x2 = acc[ai][bj][m][1][j] * rs;
;                             GAS bf16_t* p = (GAS bf16_t*)(qm + ((size_t)(b * 8 + head) * S + sq) * 192 + 128);
;                             p[i] = f2bf(x1 * cs.x - x2 * cs.y); p[32 + i] = f2bf(x2 * cs.x + x1 * cs.y);
;                         }
	v_add_f32_e32 v242, v237, v236
	v_add_f32_e32 v243, v238, v239
	v_add_f32_e32 v244, v222, v223
	v_add_f32_e32 v245, v220, v221
	v_add_f32_e32 v242, v242, v243
	v_add_f32_e32 v242, v242, v245
	v_add_f32_e32 v242, v244, v242
	v_fmamk_f32 v242, v242, 0x3b000000, v201
	v_cmp_gt_f32_e32 vcc, s33, v242
	v_mul_f32_e32 v243, 0x4b800000, v242
	s_nop 0
	v_cndmask_b32_e32 v242, v242, v243, vcc
	v_rsq_f32_e32 v242, v242
	s_nop 0
	v_mul_f32_e32 v243, 0x45800000, v242
	v_cndmask_b32_e32 v181, v242, v243, vcc
	v_add_u32_e32 v240, 0xb1, v134
	v_ashrrev_i32_e32 v241, 31, v240
	v_lshlrev_b64 v[240:241], 5, v[240:241]
	v_lshl_add_u64 v[240:241], s[46:47], 0, v[240:241]
	global_load_dwordx4 v[208:211], v[240:241], off offset:16
	global_load_dwordx4 v[224:227], v[240:241], off
	v_add_u32_e32 v240, 0xb2, v134
	v_ashrrev_i32_e32 v241, 31, v240
	v_lshlrev_b64 v[240:241], 5, v[240:241]
	v_lshl_add_u64 v[240:241], s[46:47], 0, v[240:241]
	global_load_dwordx4 v[212:215], v[240:241], off offset:16
	global_load_dwordx4 v[228:231], v[240:241], off
	v_add_u32_e32 v240, 0xb3, v134
	v_ashrrev_i32_e32 v241, 31, v240
	v_lshlrev_b64 v[240:241], 5, v[240:241]
	v_lshl_add_u64 v[240:241], s[46:47], 0, v[240:241]
	global_load_dwordx4 v[216:219], v[240:241], off offset:16
	global_load_dwordx4 v[232:235], v[240:241], off
	s_waitcnt vmcnt(4)
	v_add_f32_e32 v242, v225, v224
	v_add_f32_e32 v243, v226, v227
	v_add_f32_e32 v244, v210, v211
	v_add_f32_e32 v245, v208, v209
	v_add_f32_e32 v242, v242, v243
	v_add_f32_e32 v242, v242, v245
	v_add_f32_e32 v242, v244, v242
	v_fmamk_f32 v242, v242, 0x3b000000, v201
	v_cmp_gt_f32_e32 vcc, s33, v242
	v_mul_f32_e32 v243, 0x4b800000, v242
	s_nop 0
	v_cndmask_b32_e32 v242, v242, v243, vcc
	v_rsq_f32_e32 v242, v242
	s_nop 0
	v_mul_f32_e32 v243, 0x45800000, v242
	v_cndmask_b32_e32 v182, v242, v243, vcc
	s_waitcnt vmcnt(2)
	v_add_f32_e32 v242, v229, v228
	v_add_f32_e32 v243, v230, v231
	v_add_f32_e32 v244, v214, v215
	v_add_f32_e32 v245, v212, v213
	v_add_f32_e32 v242, v242, v243
	v_add_f32_e32 v242, v242, v245
	v_add_f32_e32 v242, v244, v242
	v_fmamk_f32 v242, v242, 0x3b000000, v201
	v_cmp_gt_f32_e32 vcc, s33, v242
	v_mul_f32_e32 v243, 0x4b800000, v242
	s_nop 0
	v_cndmask_b32_e32 v242, v242, v243, vcc
	v_rsq_f32_e32 v242, v242
	s_nop 0
	v_mul_f32_e32 v243, 0x45800000, v242
	v_cndmask_b32_e32 v183, v242, v243, vcc
	s_waitcnt vmcnt(0)
	v_add_f32_e32 v242, v233, v232
	v_add_f32_e32 v243, v234, v235
	v_add_f32_e32 v244, v218, v219
	v_add_f32_e32 v245, v216, v217
	v_add_f32_e32 v242, v242, v243
	v_add_f32_e32 v242, v242, v245
	v_add_f32_e32 v242, v244, v242
	v_fmamk_f32 v242, v242, 0x3b000000, v201
	v_cmp_gt_f32_e32 vcc, s33, v242
	v_mul_f32_e32 v243, 0x4b800000, v242
	s_nop 0
	v_cndmask_b32_e32 v242, v242, v243, vcc
	v_rsq_f32_e32 v242, v242
	s_nop 0
	v_mul_f32_e32 v243, 0x45800000, v242
	v_cndmask_b32_e32 v184, v242, v243, vcc
	v_lshlrev_b64 v[136:137], 5, v[134:135]
	v_lshl_add_u64 v[144:145], s[46:47], 0, v[136:137]
	global_load_dwordx4 v[136:139], v[144:145], off offset:16
	s_nop 0
	global_load_dwordx4 v[144:147], v[144:145], off
	s_cmp_gt_i32 s16, 3
	s_cselect_b64 s[54:55], -1, 0
	s_add_i32 s12, s40, 0xfffffc00
	s_lshr_b32 s13, s12, 6
	s_ashr_i32 s12, s17, 1
	s_and_b32 s12, s12, -8
	v_lshrrev_b32_e32 v2, 6, v132
	v_lshrrev_b32_e32 v132, 1, v141
	s_add_i32 s13, s13, s12
	v_or_b32_e32 v132, s13, v132
	s_movk_i32 s13, 0xfcc
	v_bitop3_b32 v143, v133, s13, v1 bitop3:0xc8
	v_lshlrev_b32_e32 v2, 4, v2
	v_and_or_b32 v2, v2, 16, v140
	s_mov_b64 s[40:41], -1
	s_waitcnt vmcnt(0)
	v_mov_b32_e32 v148, v145
	v_mov_b32_e32 v149, v146
	v_mov_b32_e32 v145, v147
	v_pk_add_f32 v[144:145], v[148:149], v[144:145]
	v_mov_b32_e32 v146, v138
	v_mov_b32_e32 v147, v136
	v_mov_b32_e32 v136, v139
	v_pk_add_f32 v[136:137], v[146:147], v[136:137]
	v_add_f32_e32 v1, v144, v145
	v_add_f32_e32 v1, v1, v137
	v_add_f32_e32 v1, v136, v1
	v_fmamk_f32 v1, v1, 0x3b000000, v201
	v_cmp_gt_f32_e32 vcc, s33, v1
	v_mul_f32_e32 v133, 0x4b800000, v1
	v_or_b32_e32 v138, 2, v132
	v_cndmask_b32_e32 v1, v1, v133, vcc
	v_rsq_f32_e32 v1, v1
	v_lshlrev_b32_e32 v136, 1, v2
	v_ashrrev_i32_e32 v139, 31, v138
	v_mul_f32_e32 v133, 0x45800000, v1
	v_cndmask_b32_e32 v142, v1, v133, vcc
	s_and_b64 vcc, exec, s[54:55]
	v_ashrrev_i32_e32 v133, 31, v132
	v_lshlrev_b32_e32 v1, 3, v2
	s_cbranch_vccz .LBB0_753
	v_lshl_or_b32 v2, v143, 8, v1
	v_lshl_add_u64 v[144:145], s[50:51], 0, v[2:3]
	flat_load_dwordx2 v[144:145], v[144:145]
	v_lshlrev_b64 v[146:147], 12, v[132:133]
	v_mul_f32_e32 v135, v116, v142
	v_or_b32_e32 v137, v146, v143
	v_mov_b64_e32 v[148:149], s[48:49]
	v_mul_f32_e32 v2, v120, v142
	v_mad_u64_u32 v[150:151], s[28:29], v137, s69, v[148:149]
	v_mad_i32_i24 v151, v147, s69, v151
	s_mov_b64 s[40:41], 0
	s_waitcnt vmcnt(0) lgkmcnt(0)
	v_mul_f32_e32 v137, v135, v145
	v_fma_f32 v137, v2, v144, -v137
	v_mul_f32_e32 v2, v2, v145
	v_cvt_pk_bf16_f32 v152, v137, s0
	v_mov_b32_e32 v137, v3
	v_fmac_f32_e32 v2, v135, v144
	v_lshl_add_u64 v[146:147], v[150:151], 0, v[136:137]
	v_cvt_pk_bf16_f32 v2, v2, s0
	global_store_short v[146:147], v152, off offset:256
	global_store_short v[146:147], v2, off offset:320
	v_lshlrev_b64 v[146:147], 12, v[138:139]
	v_mul_f32_e32 v135, v128, v142
	v_or_b32_e32 v146, v146, v143
	v_mul_f32_e32 v2, v124, v142
	v_mad_u64_u32 v[148:149], s[28:29], v146, s69, v[148:149]
	v_mul_f32_e32 v146, v135, v145
	v_fma_f32 v146, v2, v144, -v146
	v_mul_f32_e32 v2, v2, v145
	v_mad_i32_i24 v149, v147, s69, v149
	v_fmac_f32_e32 v2, v135, v144
	v_cvt_pk_bf16_f32 v150, v146, s0
	v_lshl_add_u64 v[146:147], v[148:149], 0, v[136:137]
	v_cvt_pk_bf16_f32 v2, v2, s0
	global_store_short v[146:147], v150, off offset:256
	global_store_short v[146:147], v2, off offset:320

; #define GAS __attribute__((address_space(1)))
; __device__ __forceinline__ unsigned cvtpk(float lo, float hi) { return __builtin_bit_cast(unsigned, __builtin_convertvector(f32x2_cv{lo, hi}, bf16x2_cv)); }
; __device__ __forceinline__ bf16_t f2bf(float f) { return (bf16_t)(cvtpk(f, 0.f) & 0xffffu); }
;     __device__ __forceinline__ void operator()(const f32x4 (&acc)[2][2][4][2], int brow, int bcol, int wr, int wc, int fr, int fq) const {
;     ...
;                     const float rs = rstd_from_ssq(ssq, row);
;                     if (bcol < 1024) {
; #pragma unroll
;                         for (int bj = 0; bj < 2; ++bj)
;                             *(GAS unsigned*)(qm + ((size_t)(b * 8 + (bcol >> 7) + bj) * S + sq) * 192 + wc * 32 + 2 * fr) = cvtpk(acc[ai][bj][m][0][j] * rs, acc[ai][bj][m][1][j] * rs);
;                     } else {
;                         const int i = (wc & 1) * 16 + fr;
;                         const float2 cs = r64[sq * 32 + i];
; #pragma unroll
;                         for (int bj = 0; bj < 2; ++bj) {
;                             const int head = ((bcol - 1024) >> 8) * 4 + bj * 2 + (wc >> 1);
;                             const float x1 = acc[ai][bj][m][0][j] * rs, x2 = acc[ai][bj][m][1][j] * rs;
;                             GAS bf16_t* p = (GAS bf16_t*)(qm + ((size_t)(b * 8 + head) * S + sq) * 192 + 128);
;                             p[i] = f2bf(x1 * cs.x - x2 * cs.y); p[32 + i] = f2bf(x2 * cs.x + x1 * cs.y);
;                         }
.LBB0_755:
	v_or_b32_e32 v142, 1, v134
	s_movk_i32 s12, 0xfcd
	v_bitop3_b32 v124, v134, s12, 1 bitop3:0xc8
	s_mov_b64 s[40:41], -1
	v_mov_b32_e32 v120, v154
	v_cndmask_b32_e64 v2, 0, 1, s[54:55]
	v_cmp_ne_u32_e64 s[42:43], 1, v2
	s_andn2_b64 vcc, exec, s[54:55]
	s_cbranch_vccnz .LBB0_757
	v_lshl_or_b32 v2, v124, 8, v1
	v_lshl_add_u64 v[142:143], s[50:51], 0, v[2:3]
	flat_load_dwordx2 v[142:143], v[142:143]
	v_lshlrev_b64 v[144:145], 12, v[132:133]
	v_mul_f32_e32 v116, v117, v120
	v_or_b32_e32 v128, v144, v124
	v_mov_b64_e32 v[146:147], s[48:49]
	v_mul_f32_e32 v2, v121, v120
	v_mad_u64_u32 v[148:149], s[12:13], v128, s69, v[146:147]
	v_mad_i32_i24 v149, v145, s69, v149
	v_mov_b32_e32 v137, v3
	v_lshl_add_u64 v[144:145], v[148:149], 0, v[136:137]
	s_mov_b64 s[40:41], 0
	s_waitcnt vmcnt(0) lgkmcnt(0)
	v_mul_f32_e32 v128, v116, v143
	v_fma_f32 v128, v2, v142, -v128
	v_mul_f32_e32 v2, v2, v143
	v_fmac_f32_e32 v2, v116, v142
	v_cvt_pk_bf16_f32 v128, v128, s0
	v_cvt_pk_bf16_f32 v2, v2, s0
	global_store_short v[144:145], v128, off offset:256
	global_store_short v[144:145], v2, off offset:320
	v_lshlrev_b64 v[144:145], 12, v[138:139]
	v_mul_f32_e32 v116, v129, v120
	v_or_b32_e32 v128, v144, v124
	v_mul_f32_e32 v2, v125, v120
	v_mad_u64_u32 v[146:147], s[12:13], v128, s69, v[146:147]
	v_mul_f32_e32 v128, v116, v143
	v_fma_f32 v128, v2, v142, -v128
	v_mul_f32_e32 v2, v2, v143
	v_mad_i32_i24 v147, v145, s69, v147
	v_fmac_f32_e32 v2, v116, v142
	v_cvt_pk_bf16_f32 v128, v128, s0
	v_lshl_add_u64 v[144:145], v[146:147], 0, v[136:137]
	v_cvt_pk_bf16_f32 v2, v2, s0
	global_store_short v[144:145], v128, off offset:256
	global_store_short v[144:145], v2, off offset:320

; #define GAS __attribute__((address_space(1)))
; __device__ __forceinline__ unsigned cvtpk(float lo, float hi) { return __builtin_bit_cast(unsigned, __builtin_convertvector(f32x2_cv{lo, hi}, bf16x2_cv)); }
; __device__ __forceinline__ bf16_t f2bf(float f) { return (bf16_t)(cvtpk(f, 0.f) & 0xffffu); }
;     __device__ __forceinline__ void operator()(const f32x4 (&acc)[2][2][4][2], int brow, int bcol, int wr, int wc, int fr, int fq) const {
;     ...
;                     const float rs = rstd_from_ssq(ssq, row);
;                     if (bcol < 1024) {
; #pragma unroll
;                         for (int bj = 0; bj < 2; ++bj)
;                             *(GAS unsigned*)(qm + ((size_t)(b * 8 + (bcol >> 7) + bj) * S + sq) * 192 + wc * 32 + 2 * fr) = cvtpk(acc[ai][bj][m][0][j] * rs, acc[ai][bj][m][1][j] * rs);
;                     } else {
;                         const int i = (wc & 1) * 16 + fr;
;                         const float2 cs = r64[sq * 32 + i];
; #pragma unroll
;                         for (int bj = 0; bj < 2; ++bj) {
;                             const int head = ((bcol - 1024) >> 8) * 4 + bj * 2 + (wc >> 1);
;                             const float x1 = acc[ai][bj][m][0][j] * rs, x2 = acc[ai][bj][m][1][j] * rs;
;                             GAS bf16_t* p = (GAS bf16_t*)(qm + ((size_t)(b * 8 + head) * S + sq) * 192 + 128);
;                             p[i] = f2bf(x1 * cs.x - x2 * cs.y); p[32 + i] = f2bf(x2 * cs.x + x1 * cs.y);
;                         }
.LBB0_759:
	v_or_b32_e32 v120, 2, v134
	s_movk_i32 s12, 0xfce
	v_bitop3_b32 v117, v134, s12, 2 bitop3:0xc8
	s_mov_b64 s[12:13], -1
	v_mov_b32_e32 v116, v155
	s_and_b64 vcc, exec, s[42:43]
	s_cbranch_vccnz .LBB0_761
	v_lshl_or_b32 v2, v117, 8, v1
	v_lshl_add_u64 v[120:121], s[50:51], 0, v[2:3]
	flat_load_dwordx2 v[120:121], v[120:121]
	v_lshlrev_b64 v[124:125], 12, v[132:133]
	v_mul_f32_e32 v135, v118, v116
	v_or_b32_e32 v124, v124, v117
	v_mov_b64_e32 v[128:129], s[48:49]
	v_mul_f32_e32 v2, v122, v116
	v_mad_u64_u32 v[142:143], s[12:13], v124, s69, v[128:129]
	v_mad_i32_i24 v143, v125, s69, v143
	v_mov_b32_e32 v137, v3
	s_waitcnt vmcnt(0) lgkmcnt(0)
	v_mul_f32_e32 v124, v135, v121
	v_fma_f32 v124, v2, v120, -v124
	v_mul_f32_e32 v2, v2, v121
	v_fmac_f32_e32 v2, v135, v120
	v_cvt_pk_bf16_f32 v144, v124, s0
	v_lshl_add_u64 v[124:125], v[142:143], 0, v[136:137]
	v_cvt_pk_bf16_f32 v2, v2, s0
	global_store_short v[124:125], v144, off offset:256
	global_store_short v[124:125], v2, off offset:320
	v_lshlrev_b64 v[124:125], 12, v[138:139]
	v_mul_f32_e32 v135, v130, v116
	v_or_b32_e32 v124, v124, v117
	v_mul_f32_e32 v2, v126, v116
	v_mad_u64_u32 v[128:129], s[12:13], v124, s69, v[128:129]
	v_mul_f32_e32 v124, v135, v121
	v_fma_f32 v124, v2, v120, -v124
	v_mul_f32_e32 v2, v2, v121
	v_mad_i32_i24 v129, v125, s69, v129
	v_fmac_f32_e32 v2, v135, v120
	v_cvt_pk_bf16_f32 v142, v124, s0
	v_lshl_add_u64 v[124:125], v[128:129], 0, v[136:137]
	v_cvt_pk_bf16_f32 v2, v2, s0
	s_mov_b64 s[12:13], 0
	global_store_short v[124:125], v142, off offset:256
	global_store_short v[124:125], v2, off offset:320

; #define GAS __attribute__((address_space(1)))
; __device__ __forceinline__ unsigned cvtpk(float lo, float hi) { return __builtin_bit_cast(unsigned, __builtin_convertvector(f32x2_cv{lo, hi}, bf16x2_cv)); }
; __device__ __forceinline__ bf16_t f2bf(float f) { return (bf16_t)(cvtpk(f, 0.f) & 0xffffu); }
;     __device__ __forceinline__ void operator()(const f32x4 (&acc)[2][2][4][2], int brow, int bcol, int wr, int wc, int fr, int fq) const {
;     ...
;                     const float rs = rstd_from_ssq(ssq, row);
;                     if (bcol < 1024) {
; #pragma unroll
;                         for (int bj = 0; bj < 2; ++bj)
;                             *(GAS unsigned*)(qm + ((size_t)(b * 8 + (bcol >> 7) + bj) * S + sq) * 192 + wc * 32 + 2 * fr) = cvtpk(acc[ai][bj][m][0][j] * rs, acc[ai][bj][m][1][j] * rs);
;                     } else {
;                         const int i = (wc & 1) * 16 + fr;
;                         const float2 cs = r64[sq * 32 + i];
; #pragma unroll
;                         for (int bj = 0; bj < 2; ++bj) {
;                             const int head = ((bcol - 1024) >> 8) * 4 + bj * 2 + (wc >> 1);
;                             const float x1 = acc[ai][bj][m][0][j] * rs, x2 = acc[ai][bj][m][1][j] * rs;
;                             GAS bf16_t* p = (GAS bf16_t*)(qm + ((size_t)(b * 8 + head) * S + sq) * 192 + 128);
;                             p[i] = f2bf(x1 * cs.x - x2 * cs.y); p[32 + i] = f2bf(x2 * cs.x + x1 * cs.y);
;                         }
.LBB0_763:
	v_or_b32_e32 v120, 3, v134
	s_movk_i32 s12, 0xfcf
	v_bitop3_b32 v117, v134, s12, 3 bitop3:0xc8
	s_mov_b64 s[12:13], -1
	v_mov_b32_e32 v116, v156
	s_and_b64 vcc, exec, s[42:43]
	s_cbranch_vccnz .LBB0_765
	v_lshl_or_b32 v2, v117, 8, v1
	v_lshl_add_u64 v[120:121], s[50:51], 0, v[2:3]
	flat_load_dwordx2 v[120:121], v[120:121]
	v_lshlrev_b64 v[124:125], 12, v[132:133]
	v_mul_f32_e32 v118, v119, v116
	v_or_b32_e32 v122, v124, v117
	v_mov_b64_e32 v[128:129], s[48:49]
	v_mul_f32_e32 v2, v123, v116
	v_mad_u64_u32 v[142:143], s[12:13], v122, s69, v[128:129]
	v_mad_i32_i24 v143, v125, s69, v143
	v_mov_b32_e32 v137, v3
	v_lshl_add_u64 v[124:125], v[142:143], 0, v[136:137]
	s_waitcnt vmcnt(0) lgkmcnt(0)
	v_mul_f32_e32 v122, v118, v121
	v_fma_f32 v122, v2, v120, -v122
	v_mul_f32_e32 v2, v2, v121
	v_fmac_f32_e32 v2, v118, v120
	v_cvt_pk_bf16_f32 v122, v122, s0
	v_cvt_pk_bf16_f32 v2, v2, s0
	global_store_short v[124:125], v122, off offset:256
	global_store_short v[124:125], v2, off offset:320
	v_lshlrev_b64 v[124:125], 12, v[138:139]
	v_mul_f32_e32 v118, v131, v116
	v_or_b32_e32 v122, v124, v117
	v_mul_f32_e32 v2, v127, v116
	v_mad_u64_u32 v[128:129], s[12:13], v122, s69, v[128:129]
	v_mul_f32_e32 v122, v118, v121
	v_fma_f32 v122, v2, v120, -v122
	v_mul_f32_e32 v2, v2, v121
	v_mad_i32_i24 v129, v125, s69, v129
	v_fmac_f32_e32 v2, v118, v120
	v_cvt_pk_bf16_f32 v122, v122, s0
	v_lshl_add_u64 v[124:125], v[128:129], 0, v[136:137]
	v_cvt_pk_bf16_f32 v2, v2, s0
	s_mov_b64 s[12:13], 0
	global_store_short v[124:125], v122, off offset:256
	global_store_short v[124:125], v2, off offset:320

; #define GAS __attribute__((address_space(1)))
; __device__ __forceinline__ unsigned cvtpk(float lo, float hi) { return __builtin_bit_cast(unsigned, __builtin_convertvector(f32x2_cv{lo, hi}, bf16x2_cv)); }
; __device__ __forceinline__ bf16_t f2bf(float f) { return (bf16_t)(cvtpk(f, 0.f) & 0xffffu); }
;     __device__ __forceinline__ void operator()(const f32x4 (&acc)[2][2][4][2], int brow, int bcol, int wr, int wc, int fr, int fq) const {
;     ...
;                     const float rs = rstd_from_ssq(ssq, row);
;                     if (bcol < 1024) {
; #pragma unroll
;                         for (int bj = 0; bj < 2; ++bj)
;                             *(GAS unsigned*)(qm + ((size_t)(b * 8 + (bcol >> 7) + bj) * S + sq) * 192 + wc * 32 + 2 * fr) = cvtpk(acc[ai][bj][m][0][j] * rs, acc[ai][bj][m][1][j] * rs);
;                     } else {
;                         const int i = (wc & 1) * 16 + fr;
;                         const float2 cs = r64[sq * 32 + i];
; #pragma unroll
;                         for (int bj = 0; bj < 2; ++bj) {
;                             const int head = ((bcol - 1024) >> 8) * 4 + bj * 2 + (wc >> 1);
;                             const float x1 = acc[ai][bj][m][0][j] * rs, x2 = acc[ai][bj][m][1][j] * rs;
;                             GAS bf16_t* p = (GAS bf16_t*)(qm + ((size_t)(b * 8 + head) * S + sq) * 192 + 128);
;                             p[i] = f2bf(x1 * cs.x - x2 * cs.y); p[32 + i] = f2bf(x2 * cs.x + x1 * cs.y);
;                         }
.LBB0_767:
	v_or_b32_e32 v118, 16, v134
	s_movk_i32 s12, 0xfdc
	v_bitop3_b32 v117, v134, s12, 16 bitop3:0xc8
	s_mov_b64 s[12:13], -1
	v_mov_b32_e32 v116, v157
	s_and_b64 vcc, exec, s[42:43]
	s_cbranch_vccnz .LBB0_769
	v_lshl_or_b32 v2, v117, 8, v1
	v_lshl_add_u64 v[118:119], s[50:51], 0, v[2:3]
	flat_load_dwordx2 v[118:119], v[118:119]
	v_lshlrev_b64 v[120:121], 12, v[132:133]
	v_mul_f32_e32 v126, v100, v116
	v_or_b32_e32 v120, v120, v117
	v_mov_b64_e32 v[122:123], s[48:49]
	v_mul_f32_e32 v2, v104, v116
	v_mad_u64_u32 v[124:125], s[12:13], v120, s69, v[122:123]
	v_mad_i32_i24 v125, v121, s69, v125
	v_mov_b32_e32 v137, v3
	s_waitcnt vmcnt(0) lgkmcnt(0)
	v_mul_f32_e32 v120, v126, v119
	v_fma_f32 v120, v2, v118, -v120
	v_mul_f32_e32 v2, v2, v119
	v_fmac_f32_e32 v2, v126, v118
	v_cvt_pk_bf16_f32 v127, v120, s0
	v_lshl_add_u64 v[120:121], v[124:125], 0, v[136:137]
	v_cvt_pk_bf16_f32 v2, v2, s0
	global_store_short v[120:121], v127, off offset:256
	global_store_short v[120:121], v2, off offset:320
	v_lshlrev_b64 v[120:121], 12, v[138:139]
	v_mul_f32_e32 v124, v112, v116
	v_or_b32_e32 v120, v120, v117
	v_mul_f32_e32 v2, v108, v116
	v_mad_u64_u32 v[122:123], s[12:13], v120, s69, v[122:123]
	v_mul_f32_e32 v120, v124, v119
	v_fma_f32 v120, v2, v118, -v120
	v_mul_f32_e32 v2, v2, v119
	v_mad_i32_i24 v123, v121, s69, v123
	v_fmac_f32_e32 v2, v124, v118
	v_cvt_pk_bf16_f32 v125, v120, s0
	v_lshl_add_u64 v[120:121], v[122:123], 0, v[136:137]
	v_cvt_pk_bf16_f32 v2, v2, s0
	s_mov_b64 s[12:13], 0
	global_store_short v[120:121], v125, off offset:256
	global_store_short v[120:121], v2, off offset:320

; #define GAS __attribute__((address_space(1)))
; __device__ __forceinline__ unsigned cvtpk(float lo, float hi) { return __builtin_bit_cast(unsigned, __builtin_convertvector(f32x2_cv{lo, hi}, bf16x2_cv)); }
; __device__ __forceinline__ bf16_t f2bf(float f) { return (bf16_t)(cvtpk(f, 0.f) & 0xffffu); }
;     __device__ __forceinline__ void operator()(const f32x4 (&acc)[2][2][4][2], int brow, int bcol, int wr, int wc, int fr, int fq) const {
;     ...
;                     const float rs = rstd_from_ssq(ssq, row);
;                     if (bcol < 1024) {
; #pragma unroll
;                         for (int bj = 0; bj < 2; ++bj)
;                             *(GAS unsigned*)(qm + ((size_t)(b * 8 + (bcol >> 7) + bj) * S + sq) * 192 + wc * 32 + 2 * fr) = cvtpk(acc[ai][bj][m][0][j] * rs, acc[ai][bj][m][1][j] * rs);
;                     } else {
;                         const int i = (wc & 1) * 16 + fr;
;                         const float2 cs = r64[sq * 32 + i];
; #pragma unroll
;                         for (int bj = 0; bj < 2; ++bj) {
;                             const int head = ((bcol - 1024) >> 8) * 4 + bj * 2 + (wc >> 1);
;                             const float x1 = acc[ai][bj][m][0][j] * rs, x2 = acc[ai][bj][m][1][j] * rs;
;                             GAS bf16_t* p = (GAS bf16_t*)(qm + ((size_t)(b * 8 + head) * S + sq) * 192 + 128);
;                             p[i] = f2bf(x1 * cs.x - x2 * cs.y); p[32 + i] = f2bf(x2 * cs.x + x1 * cs.y);
;                         }
.LBB0_771:
	v_or_b32_e32 v116, 17, v134
	s_movk_i32 s12, 0xfdd
	v_bitop3_b32 v108, v134, s12, 17 bitop3:0xc8
	s_mov_b64 s[12:13], -1
	v_mov_b32_e32 v104, v158
	s_and_b64 vcc, exec, s[42:43]
	s_cbranch_vccnz .LBB0_773
	v_lshl_or_b32 v2, v108, 8, v1
	v_lshl_add_u64 v[116:117], s[50:51], 0, v[2:3]
	flat_load_dwordx2 v[116:117], v[116:117]
	v_lshlrev_b64 v[118:119], 12, v[132:133]
	v_mul_f32_e32 v100, v101, v104
	v_or_b32_e32 v112, v118, v108
	v_mov_b64_e32 v[120:121], s[48:49]
	v_mul_f32_e32 v2, v105, v104
	v_mad_u64_u32 v[122:123], s[12:13], v112, s69, v[120:121]
	v_mad_i32_i24 v123, v119, s69, v123
	v_mov_b32_e32 v137, v3
	v_lshl_add_u64 v[118:119], v[122:123], 0, v[136:137]
	s_waitcnt vmcnt(0) lgkmcnt(0)
	v_mul_f32_e32 v112, v100, v117
	v_fma_f32 v112, v2, v116, -v112
	v_mul_f32_e32 v2, v2, v117
	v_fmac_f32_e32 v2, v100, v116
	v_cvt_pk_bf16_f32 v112, v112, s0
	v_cvt_pk_bf16_f32 v2, v2, s0
	global_store_short v[118:119], v112, off offset:256
	global_store_short v[118:119], v2, off offset:320
	v_lshlrev_b64 v[118:119], 12, v[138:139]
	v_mul_f32_e32 v100, v113, v104
	v_or_b32_e32 v112, v118, v108
	v_mul_f32_e32 v2, v109, v104
	v_mad_u64_u32 v[120:121], s[12:13], v112, s69, v[120:121]
	v_mul_f32_e32 v112, v100, v117
	v_fma_f32 v112, v2, v116, -v112
	v_mul_f32_e32 v2, v2, v117
	v_mad_i32_i24 v121, v119, s69, v121
	v_fmac_f32_e32 v2, v100, v116
	v_cvt_pk_bf16_f32 v112, v112, s0
	v_lshl_add_u64 v[118:119], v[120:121], 0, v[136:137]
	v_cvt_pk_bf16_f32 v2, v2, s0
	s_mov_b64 s[12:13], 0
	global_store_short v[118:119], v112, off offset:256
	global_store_short v[118:119], v2, off offset:320

; #define GAS __attribute__((address_space(1)))
; __device__ __forceinline__ unsigned cvtpk(float lo, float hi) { return __builtin_bit_cast(unsigned, __builtin_convertvector(f32x2_cv{lo, hi}, bf16x2_cv)); }
; __device__ __forceinline__ bf16_t f2bf(float f) { return (bf16_t)(cvtpk(f, 0.f) & 0xffffu); }
;     __device__ __forceinline__ void operator()(const f32x4 (&acc)[2][2][4][2], int brow, int bcol, int wr, int wc, int fr, int fq) const {
;     ...
;                     const float rs = rstd_from_ssq(ssq, row);
;                     if (bcol < 1024) {
; #pragma unroll
;                         for (int bj = 0; bj < 2; ++bj)
;                             *(GAS unsigned*)(qm + ((size_t)(b * 8 + (bcol >> 7) + bj) * S + sq) * 192 + wc * 32 + 2 * fr) = cvtpk(acc[ai][bj][m][0][j] * rs, acc[ai][bj][m][1][j] * rs);
;                     } else {
;                         const int i = (wc & 1) * 16 + fr;
;                         const float2 cs = r64[sq * 32 + i];
; #pragma unroll
;                         for (int bj = 0; bj < 2; ++bj) {
;                             const int head = ((bcol - 1024) >> 8) * 4 + bj * 2 + (wc >> 1);
;                             const float x1 = acc[ai][bj][m][0][j] * rs, x2 = acc[ai][bj][m][1][j] * rs;
;                             GAS bf16_t* p = (GAS bf16_t*)(qm + ((size_t)(b * 8 + head) * S + sq) * 192 + 128);
;                             p[i] = f2bf(x1 * cs.x - x2 * cs.y); p[32 + i] = f2bf(x2 * cs.x + x1 * cs.y);
;                         }
.LBB0_775:
	v_or_b32_e32 v104, 18, v134
	s_movk_i32 s12, 0xfde
	v_bitop3_b32 v101, v134, s12, 18 bitop3:0xc8
	s_mov_b64 s[12:13], -1
	v_mov_b32_e32 v100, v159
	s_and_b64 vcc, exec, s[42:43]
	s_cbranch_vccnz .LBB0_777
	v_lshl_or_b32 v2, v101, 8, v1
	v_lshl_add_u64 v[104:105], s[50:51], 0, v[2:3]
	flat_load_dwordx2 v[104:105], v[104:105]
	v_lshlrev_b64 v[108:109], 12, v[132:133]
	v_mul_f32_e32 v118, v102, v100
	v_or_b32_e32 v108, v108, v101
	v_mov_b64_e32 v[112:113], s[48:49]
	v_mul_f32_e32 v2, v106, v100
	v_mad_u64_u32 v[116:117], s[12:13], v108, s69, v[112:113]
	v_mad_i32_i24 v117, v109, s69, v117
	v_mov_b32_e32 v137, v3
	s_waitcnt vmcnt(0) lgkmcnt(0)
	v_mul_f32_e32 v108, v118, v105
	v_fma_f32 v108, v2, v104, -v108
	v_mul_f32_e32 v2, v2, v105
	v_fmac_f32_e32 v2, v118, v104
	v_cvt_pk_bf16_f32 v119, v108, s0
	v_lshl_add_u64 v[108:109], v[116:117], 0, v[136:137]
	v_cvt_pk_bf16_f32 v2, v2, s0
	global_store_short v[108:109], v119, off offset:256
	global_store_short v[108:109], v2, off offset:320
	v_lshlrev_b64 v[108:109], 12, v[138:139]
	v_mul_f32_e32 v116, v114, v100
	v_or_b32_e32 v108, v108, v101
	v_mul_f32_e32 v2, v110, v100
	v_mad_u64_u32 v[112:113], s[12:13], v108, s69, v[112:113]
	v_mul_f32_e32 v108, v116, v105
	v_fma_f32 v108, v2, v104, -v108
	v_mul_f32_e32 v2, v2, v105
	v_mad_i32_i24 v113, v109, s69, v113
	v_fmac_f32_e32 v2, v116, v104
	v_cvt_pk_bf16_f32 v117, v108, s0
	v_lshl_add_u64 v[108:109], v[112:113], 0, v[136:137]
	v_cvt_pk_bf16_f32 v2, v2, s0
	s_mov_b64 s[12:13], 0
	global_store_short v[108:109], v117, off offset:256
	global_store_short v[108:109], v2, off offset:320

; #define GAS __attribute__((address_space(1)))
; __device__ __forceinline__ unsigned cvtpk(float lo, float hi) { return __builtin_bit_cast(unsigned, __builtin_convertvector(f32x2_cv{lo, hi}, bf16x2_cv)); }
; __device__ __forceinline__ bf16_t f2bf(float f) { return (bf16_t)(cvtpk(f, 0.f) & 0xffffu); }
;     __device__ __forceinline__ void operator()(const f32x4 (&acc)[2][2][4][2], int brow, int bcol, int wr, int wc, int fr, int fq) const {
;     ...
;                     const float rs = rstd_from_ssq(ssq, row);
;                     if (bcol < 1024) {
; #pragma unroll
;                         for (int bj = 0; bj < 2; ++bj)
;                             *(GAS unsigned*)(qm + ((size_t)(b * 8 + (bcol >> 7) + bj) * S + sq) * 192 + wc * 32 + 2 * fr) = cvtpk(acc[ai][bj][m][0][j] * rs, acc[ai][bj][m][1][j] * rs);
;                     } else {
;                         const int i = (wc & 1) * 16 + fr;
;                         const float2 cs = r64[sq * 32 + i];
; #pragma unroll
;                         for (int bj = 0; bj < 2; ++bj) {
;                             const int head = ((bcol - 1024) >> 8) * 4 + bj * 2 + (wc >> 1);
;                             const float x1 = acc[ai][bj][m][0][j] * rs, x2 = acc[ai][bj][m][1][j] * rs;
;                             GAS bf16_t* p = (GAS bf16_t*)(qm + ((size_t)(b * 8 + head) * S + sq) * 192 + 128);
;                             p[i] = f2bf(x1 * cs.x - x2 * cs.y); p[32 + i] = f2bf(x2 * cs.x + x1 * cs.y);
;                         }
.LBB0_779:
	v_or_b32_e32 v104, 19, v134
	s_movk_i32 s12, 0xfdf
	v_bitop3_b32 v101, v134, s12, 19 bitop3:0xc8
	s_mov_b64 s[12:13], -1
	v_mov_b32_e32 v100, v160
	s_and_b64 vcc, exec, s[42:43]
	s_cbranch_vccnz .LBB0_781
	v_lshl_or_b32 v2, v101, 8, v1
	v_lshl_add_u64 v[104:105], s[50:51], 0, v[2:3]
	flat_load_dwordx2 v[104:105], v[104:105]
	v_lshlrev_b64 v[108:109], 12, v[132:133]
	v_mul_f32_e32 v102, v103, v100
	v_or_b32_e32 v106, v108, v101
	v_mov_b64_e32 v[112:113], s[48:49]
	v_mul_f32_e32 v2, v107, v100
	v_mad_u64_u32 v[116:117], s[12:13], v106, s69, v[112:113]
	v_mad_i32_i24 v117, v109, s69, v117
	v_mov_b32_e32 v137, v3
	v_lshl_add_u64 v[108:109], v[116:117], 0, v[136:137]
	s_waitcnt vmcnt(0) lgkmcnt(0)
	v_mul_f32_e32 v106, v102, v105
	v_fma_f32 v106, v2, v104, -v106
	v_mul_f32_e32 v2, v2, v105
	v_fmac_f32_e32 v2, v102, v104
	v_cvt_pk_bf16_f32 v106, v106, s0
	v_cvt_pk_bf16_f32 v2, v2, s0
	global_store_short v[108:109], v106, off offset:256
	global_store_short v[108:109], v2, off offset:320
	v_lshlrev_b64 v[108:109], 12, v[138:139]
	v_mul_f32_e32 v102, v115, v100
	v_or_b32_e32 v106, v108, v101
	v_mul_f32_e32 v2, v111, v100
	v_mad_u64_u32 v[112:113], s[12:13], v106, s69, v[112:113]
	v_mul_f32_e32 v106, v102, v105
	v_fma_f32 v106, v2, v104, -v106
	v_mul_f32_e32 v2, v2, v105
	v_mad_i32_i24 v113, v109, s69, v113
	v_fmac_f32_e32 v2, v102, v104
	v_cvt_pk_bf16_f32 v106, v106, s0
	v_lshl_add_u64 v[108:109], v[112:113], 0, v[136:137]
	v_cvt_pk_bf16_f32 v2, v2, s0
	s_mov_b64 s[12:13], 0
	global_store_short v[108:109], v106, off offset:256
	global_store_short v[108:109], v2, off offset:320

; #define GAS __attribute__((address_space(1)))
; __device__ __forceinline__ unsigned cvtpk(float lo, float hi) { return __builtin_bit_cast(unsigned, __builtin_convertvector(f32x2_cv{lo, hi}, bf16x2_cv)); }
; __device__ __forceinline__ bf16_t f2bf(float f) { return (bf16_t)(cvtpk(f, 0.f) & 0xffffu); }
;     __device__ __forceinline__ void operator()(const f32x4 (&acc)[2][2][4][2], int brow, int bcol, int wr, int wc, int fr, int fq) const {
;     ...
;                     const float rs = rstd_from_ssq(ssq, row);
;                     if (bcol < 1024) {
; #pragma unroll
;                         for (int bj = 0; bj < 2; ++bj)
;                             *(GAS unsigned*)(qm + ((size_t)(b * 8 + (bcol >> 7) + bj) * S + sq) * 192 + wc * 32 + 2 * fr) = cvtpk(acc[ai][bj][m][0][j] * rs, acc[ai][bj][m][1][j] * rs);
;                     } else {
;                         const int i = (wc & 1) * 16 + fr;
;                         const float2 cs = r64[sq * 32 + i];
; #pragma unroll
;                         for (int bj = 0; bj < 2; ++bj) {
;                             const int head = ((bcol - 1024) >> 8) * 4 + bj * 2 + (wc >> 1);
;                             const float x1 = acc[ai][bj][m][0][j] * rs, x2 = acc[ai][bj][m][1][j] * rs;
;                             GAS bf16_t* p = (GAS bf16_t*)(qm + ((size_t)(b * 8 + head) * S + sq) * 192 + 128);
;                             p[i] = f2bf(x1 * cs.x - x2 * cs.y); p[32 + i] = f2bf(x2 * cs.x + x1 * cs.y);
;                         }
.LBB0_783:
	v_or_b32_e32 v102, 32, v134
	s_movk_i32 s12, 0xfec
	v_bitop3_b32 v101, v134, s12, 32 bitop3:0xc8
	s_mov_b64 s[12:13], -1
	v_mov_b32_e32 v100, v161
	s_and_b64 vcc, exec, s[42:43]
	s_cbranch_vccnz .LBB0_785
	v_lshl_or_b32 v2, v101, 8, v1
	v_lshl_add_u64 v[102:103], s[50:51], 0, v[2:3]
	flat_load_dwordx2 v[102:103], v[102:103]
	v_lshlrev_b64 v[104:105], 12, v[132:133]
	v_mul_f32_e32 v110, v84, v100
	v_or_b32_e32 v104, v104, v101
	v_mov_b64_e32 v[106:107], s[48:49]
	v_mul_f32_e32 v2, v88, v100
	v_mad_u64_u32 v[108:109], s[12:13], v104, s69, v[106:107]
	v_mad_i32_i24 v109, v105, s69, v109
	v_mov_b32_e32 v137, v3
	s_waitcnt vmcnt(0) lgkmcnt(0)
	v_mul_f32_e32 v104, v110, v103
	v_fma_f32 v104, v2, v102, -v104
	v_mul_f32_e32 v2, v2, v103
	v_fmac_f32_e32 v2, v110, v102
	v_cvt_pk_bf16_f32 v111, v104, s0
	v_lshl_add_u64 v[104:105], v[108:109], 0, v[136:137]
	v_cvt_pk_bf16_f32 v2, v2, s0
	global_store_short v[104:105], v111, off offset:256
	global_store_short v[104:105], v2, off offset:320
	v_lshlrev_b64 v[104:105], 12, v[138:139]
	v_mul_f32_e32 v108, v96, v100
	v_or_b32_e32 v104, v104, v101
	v_mul_f32_e32 v2, v92, v100
	v_mad_u64_u32 v[106:107], s[12:13], v104, s69, v[106:107]
	v_mul_f32_e32 v104, v108, v103
	v_fma_f32 v104, v2, v102, -v104
	v_mul_f32_e32 v2, v2, v103
	v_mad_i32_i24 v107, v105, s69, v107
	v_fmac_f32_e32 v2, v108, v102
	v_cvt_pk_bf16_f32 v109, v104, s0
	v_lshl_add_u64 v[104:105], v[106:107], 0, v[136:137]
	v_cvt_pk_bf16_f32 v2, v2, s0
	s_mov_b64 s[12:13], 0
	global_store_short v[104:105], v109, off offset:256
	global_store_short v[104:105], v2, off offset:320

; #define GAS __attribute__((address_space(1)))
; __device__ __forceinline__ unsigned cvtpk(float lo, float hi) { return __builtin_bit_cast(unsigned, __builtin_convertvector(f32x2_cv{lo, hi}, bf16x2_cv)); }
; __device__ __forceinline__ bf16_t f2bf(float f) { return (bf16_t)(cvtpk(f, 0.f) & 0xffffu); }
;     __device__ __forceinline__ void operator()(const f32x4 (&acc)[2][2][4][2], int brow, int bcol, int wr, int wc, int fr, int fq) const {
;     ...
;                     const float rs = rstd_from_ssq(ssq, row);
;                     if (bcol < 1024) {
; #pragma unroll
;                         for (int bj = 0; bj < 2; ++bj)
;                             *(GAS unsigned*)(qm + ((size_t)(b * 8 + (bcol >> 7) + bj) * S + sq) * 192 + wc * 32 + 2 * fr) = cvtpk(acc[ai][bj][m][0][j] * rs, acc[ai][bj][m][1][j] * rs);
;                     } else {
;                         const int i = (wc & 1) * 16 + fr;
;                         const float2 cs = r64[sq * 32 + i];
; #pragma unroll
;                         for (int bj = 0; bj < 2; ++bj) {
;                             const int head = ((bcol - 1024) >> 8) * 4 + bj * 2 + (wc >> 1);
;                             const float x1 = acc[ai][bj][m][0][j] * rs, x2 = acc[ai][bj][m][1][j] * rs;
;                             GAS bf16_t* p = (GAS bf16_t*)(qm + ((size_t)(b * 8 + head) * S + sq) * 192 + 128);
;                             p[i] = f2bf(x1 * cs.x - x2 * cs.y); p[32 + i] = f2bf(x2 * cs.x + x1 * cs.y);
;                         }
.LBB0_787:
	v_or_b32_e32 v100, 33, v134
	s_movk_i32 s12, 0xfed
	v_bitop3_b32 v92, v134, s12, 33 bitop3:0xc8
	s_mov_b64 s[12:13], -1
	v_mov_b32_e32 v88, v162
	s_and_b64 vcc, exec, s[42:43]
	s_cbranch_vccnz .LBB0_789
	v_lshl_or_b32 v2, v92, 8, v1
	v_lshl_add_u64 v[100:101], s[50:51], 0, v[2:3]
	flat_load_dwordx2 v[100:101], v[100:101]
	v_lshlrev_b64 v[102:103], 12, v[132:133]
	v_mul_f32_e32 v84, v85, v88
	v_or_b32_e32 v96, v102, v92
	v_mov_b64_e32 v[104:105], s[48:49]
	v_mul_f32_e32 v2, v89, v88
	v_mad_u64_u32 v[106:107], s[12:13], v96, s69, v[104:105]
	v_mad_i32_i24 v107, v103, s69, v107
	v_mov_b32_e32 v137, v3
	v_lshl_add_u64 v[102:103], v[106:107], 0, v[136:137]
	s_waitcnt vmcnt(0) lgkmcnt(0)
	v_mul_f32_e32 v96, v84, v101
	v_fma_f32 v96, v2, v100, -v96
	v_mul_f32_e32 v2, v2, v101
	v_fmac_f32_e32 v2, v84, v100
	v_cvt_pk_bf16_f32 v96, v96, s0
	v_cvt_pk_bf16_f32 v2, v2, s0
	global_store_short v[102:103], v96, off offset:256
	global_store_short v[102:103], v2, off offset:320
	v_lshlrev_b64 v[102:103], 12, v[138:139]
	v_mul_f32_e32 v84, v97, v88
	v_or_b32_e32 v96, v102, v92
	v_mul_f32_e32 v2, v93, v88
	v_mad_u64_u32 v[104:105], s[12:13], v96, s69, v[104:105]
	v_mul_f32_e32 v96, v84, v101
	v_fma_f32 v96, v2, v100, -v96
	v_mul_f32_e32 v2, v2, v101
	v_mad_i32_i24 v105, v103, s69, v105
	v_fmac_f32_e32 v2, v84, v100
	v_cvt_pk_bf16_f32 v96, v96, s0
	v_lshl_add_u64 v[102:103], v[104:105], 0, v[136:137]
	v_cvt_pk_bf16_f32 v2, v2, s0
	s_mov_b64 s[12:13], 0
	global_store_short v[102:103], v96, off offset:256
	global_store_short v[102:103], v2, off offset:320

; #define GAS __attribute__((address_space(1)))
; __device__ __forceinline__ unsigned cvtpk(float lo, float hi) { return __builtin_bit_cast(unsigned, __builtin_convertvector(f32x2_cv{lo, hi}, bf16x2_cv)); }
; __device__ __forceinline__ bf16_t f2bf(float f) { return (bf16_t)(cvtpk(f, 0.f) & 0xffffu); }
;     __device__ __forceinline__ void operator()(const f32x4 (&acc)[2][2][4][2], int brow, int bcol, int wr, int wc, int fr, int fq) const {
;     ...
;                     const float rs = rstd_from_ssq(ssq, row);
;                     if (bcol < 1024) {
; #pragma unroll
;                         for (int bj = 0; bj < 2; ++bj)
;                             *(GAS unsigned*)(qm + ((size_t)(b * 8 + (bcol >> 7) + bj) * S + sq) * 192 + wc * 32 + 2 * fr) = cvtpk(acc[ai][bj][m][0][j] * rs, acc[ai][bj][m][1][j] * rs);
;                     } else {
;                         const int i = (wc & 1) * 16 + fr;
;                         const float2 cs = r64[sq * 32 + i];
; #pragma unroll
;                         for (int bj = 0; bj < 2; ++bj) {
;                             const int head = ((bcol - 1024) >> 8) * 4 + bj * 2 + (wc >> 1);
;                             const float x1 = acc[ai][bj][m][0][j] * rs, x2 = acc[ai][bj][m][1][j] * rs;
;                             GAS bf16_t* p = (GAS bf16_t*)(qm + ((size_t)(b * 8 + head) * S + sq) * 192 + 128);
;                             p[i] = f2bf(x1 * cs.x - x2 * cs.y); p[32 + i] = f2bf(x2 * cs.x + x1 * cs.y);
;                         }
.LBB0_791:
	v_or_b32_e32 v88, 34, v134
	s_movk_i32 s12, 0xfee
	v_bitop3_b32 v85, v134, s12, 34 bitop3:0xc8
	s_mov_b64 s[12:13], -1
	v_mov_b32_e32 v84, v163
	s_and_b64 vcc, exec, s[42:43]
	s_cbranch_vccnz .LBB0_793
	v_lshl_or_b32 v2, v85, 8, v1
	v_lshl_add_u64 v[88:89], s[50:51], 0, v[2:3]
	flat_load_dwordx2 v[88:89], v[88:89]
	v_lshlrev_b64 v[92:93], 12, v[132:133]
	v_mul_f32_e32 v102, v86, v84
	v_or_b32_e32 v92, v92, v85
	v_mov_b64_e32 v[96:97], s[48:49]
	v_mul_f32_e32 v2, v90, v84
	v_mad_u64_u32 v[100:101], s[12:13], v92, s69, v[96:97]
	v_mad_i32_i24 v101, v93, s69, v101
	v_mov_b32_e32 v137, v3
	s_waitcnt vmcnt(0) lgkmcnt(0)
	v_mul_f32_e32 v92, v102, v89
	v_fma_f32 v92, v2, v88, -v92
	v_mul_f32_e32 v2, v2, v89
	v_fmac_f32_e32 v2, v102, v88
	v_cvt_pk_bf16_f32 v103, v92, s0
	v_lshl_add_u64 v[92:93], v[100:101], 0, v[136:137]
	v_cvt_pk_bf16_f32 v2, v2, s0
	global_store_short v[92:93], v103, off offset:256
	global_store_short v[92:93], v2, off offset:320
	v_lshlrev_b64 v[92:93], 12, v[138:139]
	v_mul_f32_e32 v100, v98, v84
	v_or_b32_e32 v92, v92, v85
	v_mul_f32_e32 v2, v94, v84
	v_mad_u64_u32 v[96:97], s[12:13], v92, s69, v[96:97]
	v_mul_f32_e32 v92, v100, v89
	v_fma_f32 v92, v2, v88, -v92
	v_mul_f32_e32 v2, v2, v89
	v_mad_i32_i24 v97, v93, s69, v97
	v_fmac_f32_e32 v2, v100, v88
	v_cvt_pk_bf16_f32 v101, v92, s0
	v_lshl_add_u64 v[92:93], v[96:97], 0, v[136:137]
	v_cvt_pk_bf16_f32 v2, v2, s0
	s_mov_b64 s[12:13], 0
	global_store_short v[92:93], v101, off offset:256
	global_store_short v[92:93], v2, off offset:320

; #define GAS __attribute__((address_space(1)))
; __device__ __forceinline__ unsigned cvtpk(float lo, float hi) { return __builtin_bit_cast(unsigned, __builtin_convertvector(f32x2_cv{lo, hi}, bf16x2_cv)); }
; __device__ __forceinline__ bf16_t f2bf(float f) { return (bf16_t)(cvtpk(f, 0.f) & 0xffffu); }
;     __device__ __forceinline__ void operator()(const f32x4 (&acc)[2][2][4][2], int brow, int bcol, int wr, int wc, int fr, int fq) const {
;     ...
;                     const float rs = rstd_from_ssq(ssq, row);
;                     if (bcol < 1024) {
; #pragma unroll
;                         for (int bj = 0; bj < 2; ++bj)
;                             *(GAS unsigned*)(qm + ((size_t)(b * 8 + (bcol >> 7) + bj) * S + sq) * 192 + wc * 32 + 2 * fr) = cvtpk(acc[ai][bj][m][0][j] * rs, acc[ai][bj][m][1][j] * rs);
;                     } else {
;                         const int i = (wc & 1) * 16 + fr;
;                         const float2 cs = r64[sq * 32 + i];
; #pragma unroll
;                         for (int bj = 0; bj < 2; ++bj) {
;                             const int head = ((bcol - 1024) >> 8) * 4 + bj * 2 + (wc >> 1);
;                             const float x1 = acc[ai][bj][m][0][j] * rs, x2 = acc[ai][bj][m][1][j] * rs;
;                             GAS bf16_t* p = (GAS bf16_t*)(qm + ((size_t)(b * 8 + head) * S + sq) * 192 + 128);
;                             p[i] = f2bf(x1 * cs.x - x2 * cs.y); p[32 + i] = f2bf(x2 * cs.x + x1 * cs.y);
;                         }
.LBB0_795:
	v_or_b32_e32 v88, 35, v134
	s_movk_i32 s12, 0xfef
	v_bitop3_b32 v85, v134, s12, 35 bitop3:0xc8
	s_mov_b64 s[12:13], -1
	v_mov_b32_e32 v84, v164
	s_and_b64 vcc, exec, s[42:43]
	s_cbranch_vccnz .LBB0_797
	v_lshl_or_b32 v2, v85, 8, v1
	v_lshl_add_u64 v[88:89], s[50:51], 0, v[2:3]
	flat_load_dwordx2 v[88:89], v[88:89]
	v_lshlrev_b64 v[92:93], 12, v[132:133]
	v_mul_f32_e32 v86, v87, v84
	v_or_b32_e32 v90, v92, v85
	v_mov_b64_e32 v[96:97], s[48:49]
	v_mul_f32_e32 v2, v91, v84
	v_mad_u64_u32 v[100:101], s[12:13], v90, s69, v[96:97]
	v_mad_i32_i24 v101, v93, s69, v101
	v_mov_b32_e32 v137, v3
	v_lshl_add_u64 v[92:93], v[100:101], 0, v[136:137]
	s_waitcnt vmcnt(0) lgkmcnt(0)
	v_mul_f32_e32 v90, v86, v89
	v_fma_f32 v90, v2, v88, -v90
	v_mul_f32_e32 v2, v2, v89
	v_fmac_f32_e32 v2, v86, v88
	v_cvt_pk_bf16_f32 v90, v90, s0
	v_cvt_pk_bf16_f32 v2, v2, s0
	global_store_short v[92:93], v90, off offset:256
	global_store_short v[92:93], v2, off offset:320
	v_lshlrev_b64 v[92:93], 12, v[138:139]
	v_mul_f32_e32 v86, v99, v84
	v_or_b32_e32 v90, v92, v85
	v_mul_f32_e32 v2, v95, v84
	v_mad_u64_u32 v[96:97], s[12:13], v90, s69, v[96:97]
	v_mul_f32_e32 v90, v86, v89
	v_fma_f32 v90, v2, v88, -v90
	v_mul_f32_e32 v2, v2, v89
	v_mad_i32_i24 v97, v93, s69, v97
	v_fmac_f32_e32 v2, v86, v88
	v_cvt_pk_bf16_f32 v90, v90, s0
	v_lshl_add_u64 v[92:93], v[96:97], 0, v[136:137]
	v_cvt_pk_bf16_f32 v2, v2, s0
	s_mov_b64 s[12:13], 0
	global_store_short v[92:93], v90, off offset:256
	global_store_short v[92:93], v2, off offset:320

; #define GAS __attribute__((address_space(1)))
; __device__ __forceinline__ unsigned cvtpk(float lo, float hi) { return __builtin_bit_cast(unsigned, __builtin_convertvector(f32x2_cv{lo, hi}, bf16x2_cv)); }
; __device__ __forceinline__ bf16_t f2bf(float f) { return (bf16_t)(cvtpk(f, 0.f) & 0xffffu); }
;     __device__ __forceinline__ void operator()(const f32x4 (&acc)[2][2][4][2], int brow, int bcol, int wr, int wc, int fr, int fq) const {
;     ...
;                     const float rs = rstd_from_ssq(ssq, row);
;                     if (bcol < 1024) {
; #pragma unroll
;                         for (int bj = 0; bj < 2; ++bj)
;                             *(GAS unsigned*)(qm + ((size_t)(b * 8 + (bcol >> 7) + bj) * S + sq) * 192 + wc * 32 + 2 * fr) = cvtpk(acc[ai][bj][m][0][j] * rs, acc[ai][bj][m][1][j] * rs);
;                     } else {
;                         const int i = (wc & 1) * 16 + fr;
;                         const float2 cs = r64[sq * 32 + i];
; #pragma unroll
;                         for (int bj = 0; bj < 2; ++bj) {
;                             const int head = ((bcol - 1024) >> 8) * 4 + bj * 2 + (wc >> 1);
;                             const float x1 = acc[ai][bj][m][0][j] * rs, x2 = acc[ai][bj][m][1][j] * rs;
;                             GAS bf16_t* p = (GAS bf16_t*)(qm + ((size_t)(b * 8 + head) * S + sq) * 192 + 128);
;                             p[i] = f2bf(x1 * cs.x - x2 * cs.y); p[32 + i] = f2bf(x2 * cs.x + x1 * cs.y);
;                         }
.LBB0_799:
	v_or_b32_e32 v86, 48, v134
	s_movk_i32 s12, 0xffc
	v_bitop3_b32 v85, v134, s12, 48 bitop3:0xc8
	s_mov_b64 s[12:13], -1
	v_mov_b32_e32 v84, v165
	s_and_b64 vcc, exec, s[42:43]
	s_cbranch_vccnz .LBB0_801
	v_lshl_or_b32 v2, v85, 8, v1
	v_lshl_add_u64 v[86:87], s[50:51], 0, v[2:3]
	flat_load_dwordx2 v[86:87], v[86:87]
	v_lshlrev_b64 v[88:89], 12, v[132:133]
	v_mul_f32_e32 v94, v68, v84
	v_or_b32_e32 v88, v88, v85
	v_mov_b64_e32 v[90:91], s[48:49]
	v_mul_f32_e32 v2, v72, v84
	v_mad_u64_u32 v[92:93], s[12:13], v88, s69, v[90:91]
	v_mad_i32_i24 v93, v89, s69, v93
	v_mov_b32_e32 v137, v3
	s_waitcnt vmcnt(0) lgkmcnt(0)
	v_mul_f32_e32 v88, v94, v87
	v_fma_f32 v88, v2, v86, -v88
	v_mul_f32_e32 v2, v2, v87
	v_fmac_f32_e32 v2, v94, v86
	v_cvt_pk_bf16_f32 v95, v88, s0
	v_lshl_add_u64 v[88:89], v[92:93], 0, v[136:137]
	v_cvt_pk_bf16_f32 v2, v2, s0
	global_store_short v[88:89], v95, off offset:256
	global_store_short v[88:89], v2, off offset:320
	v_lshlrev_b64 v[88:89], 12, v[138:139]
	v_mul_f32_e32 v92, v80, v84
	v_or_b32_e32 v88, v88, v85
	v_mul_f32_e32 v2, v76, v84
	v_mad_u64_u32 v[90:91], s[12:13], v88, s69, v[90:91]
	v_mul_f32_e32 v88, v92, v87
	v_fma_f32 v88, v2, v86, -v88
	v_mul_f32_e32 v2, v2, v87
	v_mad_i32_i24 v91, v89, s69, v91
	v_fmac_f32_e32 v2, v92, v86
	v_cvt_pk_bf16_f32 v93, v88, s0
	v_lshl_add_u64 v[88:89], v[90:91], 0, v[136:137]
	v_cvt_pk_bf16_f32 v2, v2, s0
	s_mov_b64 s[12:13], 0
	global_store_short v[88:89], v93, off offset:256
	global_store_short v[88:89], v2, off offset:320

; #define GAS __attribute__((address_space(1)))
; __device__ __forceinline__ unsigned cvtpk(float lo, float hi) { return __builtin_bit_cast(unsigned, __builtin_convertvector(f32x2_cv{lo, hi}, bf16x2_cv)); }
; __device__ __forceinline__ bf16_t f2bf(float f) { return (bf16_t)(cvtpk(f, 0.f) & 0xffffu); }
;     __device__ __forceinline__ void operator()(const f32x4 (&acc)[2][2][4][2], int brow, int bcol, int wr, int wc, int fr, int fq) const {
;     ...
;                     const float rs = rstd_from_ssq(ssq, row);
;                     if (bcol < 1024) {
; #pragma unroll
;                         for (int bj = 0; bj < 2; ++bj)
;                             *(GAS unsigned*)(qm + ((size_t)(b * 8 + (bcol >> 7) + bj) * S + sq) * 192 + wc * 32 + 2 * fr) = cvtpk(acc[ai][bj][m][0][j] * rs, acc[ai][bj][m][1][j] * rs);
;                     } else {
;                         const int i = (wc & 1) * 16 + fr;
;                         const float2 cs = r64[sq * 32 + i];
; #pragma unroll
;                         for (int bj = 0; bj < 2; ++bj) {
;                             const int head = ((bcol - 1024) >> 8) * 4 + bj * 2 + (wc >> 1);
;                             const float x1 = acc[ai][bj][m][0][j] * rs, x2 = acc[ai][bj][m][1][j] * rs;
;                             GAS bf16_t* p = (GAS bf16_t*)(qm + ((size_t)(b * 8 + head) * S + sq) * 192 + 128);
;                             p[i] = f2bf(x1 * cs.x - x2 * cs.y); p[32 + i] = f2bf(x2 * cs.x + x1 * cs.y);
;                         }
.LBB0_803:
	v_or_b32_e32 v84, 49, v134
	s_movk_i32 s12, 0xffd
	v_bitop3_b32 v76, v134, s12, 49 bitop3:0xc8
	s_mov_b64 s[12:13], -1
	v_mov_b32_e32 v72, v166
	s_and_b64 vcc, exec, s[42:43]
	s_cbranch_vccnz .LBB0_805
	v_lshl_or_b32 v2, v76, 8, v1
	v_lshl_add_u64 v[84:85], s[50:51], 0, v[2:3]
	flat_load_dwordx2 v[84:85], v[84:85]
	v_lshlrev_b64 v[86:87], 12, v[132:133]
	v_mul_f32_e32 v68, v69, v72
	v_or_b32_e32 v80, v86, v76
	v_mov_b64_e32 v[88:89], s[48:49]
	v_mul_f32_e32 v2, v73, v72
	v_mad_u64_u32 v[90:91], s[12:13], v80, s69, v[88:89]
	v_mad_i32_i24 v91, v87, s69, v91
	v_mov_b32_e32 v137, v3
	v_lshl_add_u64 v[86:87], v[90:91], 0, v[136:137]
	s_waitcnt vmcnt(0) lgkmcnt(0)
	v_mul_f32_e32 v80, v68, v85
	v_fma_f32 v80, v2, v84, -v80
	v_mul_f32_e32 v2, v2, v85
	v_fmac_f32_e32 v2, v68, v84
	v_cvt_pk_bf16_f32 v80, v80, s0
	v_cvt_pk_bf16_f32 v2, v2, s0
	global_store_short v[86:87], v80, off offset:256
	global_store_short v[86:87], v2, off offset:320
	v_lshlrev_b64 v[86:87], 12, v[138:139]
	v_mul_f32_e32 v68, v81, v72
	v_or_b32_e32 v80, v86, v76
	v_mul_f32_e32 v2, v77, v72
	v_mad_u64_u32 v[88:89], s[12:13], v80, s69, v[88:89]
	v_mul_f32_e32 v80, v68, v85
	v_fma_f32 v80, v2, v84, -v80
	v_mul_f32_e32 v2, v2, v85
	v_mad_i32_i24 v89, v87, s69, v89
	v_fmac_f32_e32 v2, v68, v84
	v_cvt_pk_bf16_f32 v80, v80, s0
	v_lshl_add_u64 v[86:87], v[88:89], 0, v[136:137]
	v_cvt_pk_bf16_f32 v2, v2, s0
	s_mov_b64 s[12:13], 0
	global_store_short v[86:87], v80, off offset:256
	global_store_short v[86:87], v2, off offset:320

; #define GAS __attribute__((address_space(1)))
; __device__ __forceinline__ unsigned cvtpk(float lo, float hi) { return __builtin_bit_cast(unsigned, __builtin_convertvector(f32x2_cv{lo, hi}, bf16x2_cv)); }
; __device__ __forceinline__ bf16_t f2bf(float f) { return (bf16_t)(cvtpk(f, 0.f) & 0xffffu); }
;     __device__ __forceinline__ void operator()(const f32x4 (&acc)[2][2][4][2], int brow, int bcol, int wr, int wc, int fr, int fq) const {
;     ...
;                     const float rs = rstd_from_ssq(ssq, row);
;                     if (bcol < 1024) {
; #pragma unroll
;                         for (int bj = 0; bj < 2; ++bj)
;                             *(GAS unsigned*)(qm + ((size_t)(b * 8 + (bcol >> 7) + bj) * S + sq) * 192 + wc * 32 + 2 * fr) = cvtpk(acc[ai][bj][m][0][j] * rs, acc[ai][bj][m][1][j] * rs);
;                     } else {
;                         const int i = (wc & 1) * 16 + fr;
;                         const float2 cs = r64[sq * 32 + i];
; #pragma unroll
;                         for (int bj = 0; bj < 2; ++bj) {
;                             const int head = ((bcol - 1024) >> 8) * 4 + bj * 2 + (wc >> 1);
;                             const float x1 = acc[ai][bj][m][0][j] * rs, x2 = acc[ai][bj][m][1][j] * rs;
;                             GAS bf16_t* p = (GAS bf16_t*)(qm + ((size_t)(b * 8 + head) * S + sq) * 192 + 128);
;                             p[i] = f2bf(x1 * cs.x - x2 * cs.y); p[32 + i] = f2bf(x2 * cs.x + x1 * cs.y);
;                         }
.LBB0_807:
	v_or_b32_e32 v72, 50, v134
	s_movk_i32 s12, 0xffe
	v_bitop3_b32 v69, v134, s12, 50 bitop3:0xc8
	s_mov_b64 s[12:13], -1
	v_mov_b32_e32 v68, v167
	s_and_b64 vcc, exec, s[42:43]
	s_cbranch_vccnz .LBB0_809
	v_lshl_or_b32 v2, v69, 8, v1
	v_lshl_add_u64 v[72:73], s[50:51], 0, v[2:3]
	flat_load_dwordx2 v[72:73], v[72:73]
	v_lshlrev_b64 v[76:77], 12, v[132:133]
	v_mul_f32_e32 v86, v70, v68
	v_or_b32_e32 v76, v76, v69
	v_mov_b64_e32 v[80:81], s[48:49]
	v_mul_f32_e32 v2, v74, v68
	v_mad_u64_u32 v[84:85], s[12:13], v76, s69, v[80:81]
	v_mad_i32_i24 v85, v77, s69, v85
	v_mov_b32_e32 v137, v3
	s_waitcnt vmcnt(0) lgkmcnt(0)
	v_mul_f32_e32 v76, v86, v73
	v_fma_f32 v76, v2, v72, -v76
	v_mul_f32_e32 v2, v2, v73
	v_fmac_f32_e32 v2, v86, v72
	v_cvt_pk_bf16_f32 v87, v76, s0
	v_lshl_add_u64 v[76:77], v[84:85], 0, v[136:137]
	v_cvt_pk_bf16_f32 v2, v2, s0
	global_store_short v[76:77], v87, off offset:256
	global_store_short v[76:77], v2, off offset:320
	v_lshlrev_b64 v[76:77], 12, v[138:139]
	v_mul_f32_e32 v84, v82, v68
	v_or_b32_e32 v76, v76, v69
	v_mul_f32_e32 v2, v78, v68
	v_mad_u64_u32 v[80:81], s[12:13], v76, s69, v[80:81]
	v_mul_f32_e32 v76, v84, v73
	v_fma_f32 v76, v2, v72, -v76
	v_mul_f32_e32 v2, v2, v73
	v_mad_i32_i24 v81, v77, s69, v81
	v_fmac_f32_e32 v2, v84, v72
	v_cvt_pk_bf16_f32 v85, v76, s0
	v_lshl_add_u64 v[76:77], v[80:81], 0, v[136:137]
	v_cvt_pk_bf16_f32 v2, v2, s0
	s_mov_b64 s[12:13], 0
	global_store_short v[76:77], v85, off offset:256
	global_store_short v[76:77], v2, off offset:320

; #define GAS __attribute__((address_space(1)))
; __device__ __forceinline__ unsigned cvtpk(float lo, float hi) { return __builtin_bit_cast(unsigned, __builtin_convertvector(f32x2_cv{lo, hi}, bf16x2_cv)); }
; __device__ __forceinline__ bf16_t f2bf(float f) { return (bf16_t)(cvtpk(f, 0.f) & 0xffffu); }
;     __device__ __forceinline__ void operator()(const f32x4 (&acc)[2][2][4][2], int brow, int bcol, int wr, int wc, int fr, int fq) const {
;     ...
;                     const float rs = rstd_from_ssq(ssq, row);
;                     if (bcol < 1024) {
; #pragma unroll
;                         for (int bj = 0; bj < 2; ++bj)
;                             *(GAS unsigned*)(qm + ((size_t)(b * 8 + (bcol >> 7) + bj) * S + sq) * 192 + wc * 32 + 2 * fr) = cvtpk(acc[ai][bj][m][0][j] * rs, acc[ai][bj][m][1][j] * rs);
;                     } else {
;                         const int i = (wc & 1) * 16 + fr;
;                         const float2 cs = r64[sq * 32 + i];
; #pragma unroll
;                         for (int bj = 0; bj < 2; ++bj) {
;                             const int head = ((bcol - 1024) >> 8) * 4 + bj * 2 + (wc >> 1);
;                             const float x1 = acc[ai][bj][m][0][j] * rs, x2 = acc[ai][bj][m][1][j] * rs;
;                             GAS bf16_t* p = (GAS bf16_t*)(qm + ((size_t)(b * 8 + head) * S + sq) * 192 + 128);
;                             p[i] = f2bf(x1 * cs.x - x2 * cs.y); p[32 + i] = f2bf(x2 * cs.x + x1 * cs.y);
;                         }
.LBB0_811:
	v_or_b32_e32 v72, 51, v134
	s_movk_i32 s12, 0xfff
	v_bitop3_b32 v69, v134, s12, 51 bitop3:0xc8
	s_mov_b64 s[12:13], -1
	v_mov_b32_e32 v68, v168
	s_and_b64 vcc, exec, s[42:43]
	s_cbranch_vccnz .LBB0_813
	v_lshl_or_b32 v2, v69, 8, v1
	v_lshl_add_u64 v[72:73], s[50:51], 0, v[2:3]
	flat_load_dwordx2 v[72:73], v[72:73]
	v_lshlrev_b64 v[76:77], 12, v[132:133]
	v_mul_f32_e32 v70, v71, v68
	v_or_b32_e32 v74, v76, v69
	v_mov_b64_e32 v[80:81], s[48:49]
	v_mul_f32_e32 v2, v75, v68
	v_mad_u64_u32 v[84:85], s[12:13], v74, s69, v[80:81]
	v_mad_i32_i24 v85, v77, s69, v85
	v_mov_b32_e32 v137, v3
	v_lshl_add_u64 v[76:77], v[84:85], 0, v[136:137]
	s_waitcnt vmcnt(0) lgkmcnt(0)
	v_mul_f32_e32 v74, v70, v73
	v_fma_f32 v74, v2, v72, -v74
	v_mul_f32_e32 v2, v2, v73
	v_fmac_f32_e32 v2, v70, v72
	v_cvt_pk_bf16_f32 v74, v74, s0
	v_cvt_pk_bf16_f32 v2, v2, s0
	global_store_short v[76:77], v74, off offset:256
	global_store_short v[76:77], v2, off offset:320
	v_lshlrev_b64 v[76:77], 12, v[138:139]
	v_mul_f32_e32 v70, v83, v68
	v_or_b32_e32 v74, v76, v69
	v_mul_f32_e32 v2, v79, v68
	v_mad_u64_u32 v[80:81], s[12:13], v74, s69, v[80:81]
	v_mul_f32_e32 v74, v70, v73
	v_fma_f32 v74, v2, v72, -v74
	v_mul_f32_e32 v2, v2, v73
	v_mad_i32_i24 v81, v77, s69, v81
	v_fmac_f32_e32 v2, v70, v72
	v_cvt_pk_bf16_f32 v74, v74, s0
	v_lshl_add_u64 v[76:77], v[80:81], 0, v[136:137]
	v_cvt_pk_bf16_f32 v2, v2, s0
	s_mov_b64 s[12:13], 0
	global_store_short v[76:77], v74, off offset:256
	global_store_short v[76:77], v2, off offset:320

; #define GAS __attribute__((address_space(1)))
; __device__ __forceinline__ unsigned cvtpk(float lo, float hi) { return __builtin_bit_cast(unsigned, __builtin_convertvector(f32x2_cv{lo, hi}, bf16x2_cv)); }
; __device__ __forceinline__ bf16_t f2bf(float f) { return (bf16_t)(cvtpk(f, 0.f) & 0xffffu); }
;     __device__ __forceinline__ void operator()(const f32x4 (&acc)[2][2][4][2], int brow, int bcol, int wr, int wc, int fr, int fq) const {
;     ...
;                     const float rs = rstd_from_ssq(ssq, row);
;                     if (bcol < 1024) {
; #pragma unroll
;                         for (int bj = 0; bj < 2; ++bj)
;                             *(GAS unsigned*)(qm + ((size_t)(b * 8 + (bcol >> 7) + bj) * S + sq) * 192 + wc * 32 + 2 * fr) = cvtpk(acc[ai][bj][m][0][j] * rs, acc[ai][bj][m][1][j] * rs);
;                     } else {
;                         const int i = (wc & 1) * 16 + fr;
;                         const float2 cs = r64[sq * 32 + i];
; #pragma unroll
;                         for (int bj = 0; bj < 2; ++bj) {
;                             const int head = ((bcol - 1024) >> 8) * 4 + bj * 2 + (wc >> 1);
;                             const float x1 = acc[ai][bj][m][0][j] * rs, x2 = acc[ai][bj][m][1][j] * rs;
;                             GAS bf16_t* p = (GAS bf16_t*)(qm + ((size_t)(b * 8 + head) * S + sq) * 192 + 128);
;                             p[i] = f2bf(x1 * cs.x - x2 * cs.y); p[32 + i] = f2bf(x2 * cs.x + x1 * cs.y);
;                         }
.LBB0_815:
	v_add_u32_e32 v70, 0x80, v134
	v_and_b32_e32 v69, 0xfcc, v70
	s_mov_b64 s[12:13], -1
	v_mov_b32_e32 v68, v169
	s_and_b64 vcc, exec, s[42:43]
	s_cbranch_vccnz .LBB0_817
	v_lshl_or_b32 v2, v69, 8, v1
	v_lshl_add_u64 v[70:71], s[50:51], 0, v[2:3]
	flat_load_dwordx2 v[70:71], v[70:71]
	v_lshlrev_b64 v[72:73], 12, v[132:133]
	v_mul_f32_e32 v78, v52, v68
	v_or_b32_e32 v72, v72, v69
	v_mov_b64_e32 v[74:75], s[48:49]
	v_mul_f32_e32 v2, v56, v68
	v_mad_u64_u32 v[76:77], s[12:13], v72, s69, v[74:75]
	v_mad_i32_i24 v77, v73, s69, v77
	v_mov_b32_e32 v137, v3
	s_waitcnt vmcnt(0) lgkmcnt(0)
	v_mul_f32_e32 v72, v78, v71
	v_fma_f32 v72, v2, v70, -v72
	v_mul_f32_e32 v2, v2, v71
	v_fmac_f32_e32 v2, v78, v70
	v_cvt_pk_bf16_f32 v79, v72, s0
	v_lshl_add_u64 v[72:73], v[76:77], 0, v[136:137]
	v_cvt_pk_bf16_f32 v2, v2, s0
	global_store_short v[72:73], v79, off offset:256
	global_store_short v[72:73], v2, off offset:320
	v_lshlrev_b64 v[72:73], 12, v[138:139]
	v_mul_f32_e32 v76, v64, v68
	v_or_b32_e32 v72, v72, v69
	v_mul_f32_e32 v2, v60, v68
	v_mad_u64_u32 v[74:75], s[12:13], v72, s69, v[74:75]
	v_mul_f32_e32 v72, v76, v71
	v_fma_f32 v72, v2, v70, -v72
	v_mul_f32_e32 v2, v2, v71
	v_mad_i32_i24 v75, v73, s69, v75
	v_fmac_f32_e32 v2, v76, v70
	v_cvt_pk_bf16_f32 v77, v72, s0
	v_lshl_add_u64 v[72:73], v[74:75], 0, v[136:137]
	v_cvt_pk_bf16_f32 v2, v2, s0
	s_mov_b64 s[12:13], 0
	global_store_short v[72:73], v77, off offset:256
	global_store_short v[72:73], v2, off offset:320

; #define GAS __attribute__((address_space(1)))
; __device__ __forceinline__ unsigned cvtpk(float lo, float hi) { return __builtin_bit_cast(unsigned, __builtin_convertvector(f32x2_cv{lo, hi}, bf16x2_cv)); }
; __device__ __forceinline__ bf16_t f2bf(float f) { return (bf16_t)(cvtpk(f, 0.f) & 0xffffu); }
;     __device__ __forceinline__ void operator()(const f32x4 (&acc)[2][2][4][2], int brow, int bcol, int wr, int wc, int fr, int fq) const {
;     ...
;                     const float rs = rstd_from_ssq(ssq, row);
;                     if (bcol < 1024) {
; #pragma unroll
;                         for (int bj = 0; bj < 2; ++bj)
;                             *(GAS unsigned*)(qm + ((size_t)(b * 8 + (bcol >> 7) + bj) * S + sq) * 192 + wc * 32 + 2 * fr) = cvtpk(acc[ai][bj][m][0][j] * rs, acc[ai][bj][m][1][j] * rs);
;                     } else {
;                         const int i = (wc & 1) * 16 + fr;
;                         const float2 cs = r64[sq * 32 + i];
; #pragma unroll
;                         for (int bj = 0; bj < 2; ++bj) {
;                             const int head = ((bcol - 1024) >> 8) * 4 + bj * 2 + (wc >> 1);
;                             const float x1 = acc[ai][bj][m][0][j] * rs, x2 = acc[ai][bj][m][1][j] * rs;
;                             GAS bf16_t* p = (GAS bf16_t*)(qm + ((size_t)(b * 8 + head) * S + sq) * 192 + 128);
;                             p[i] = f2bf(x1 * cs.x - x2 * cs.y); p[32 + i] = f2bf(x2 * cs.x + x1 * cs.y);
;                         }
.LBB0_819:
	v_add_u32_e32 v68, 0x81, v134
	v_and_b32_e32 v60, 0xfcd, v68
	s_mov_b64 s[12:13], -1
	v_mov_b32_e32 v56, v170
	s_and_b64 vcc, exec, s[42:43]
	s_cbranch_vccnz .LBB0_821
	v_lshl_or_b32 v2, v60, 8, v1
	v_lshl_add_u64 v[68:69], s[50:51], 0, v[2:3]
	flat_load_dwordx2 v[68:69], v[68:69]
	v_lshlrev_b64 v[70:71], 12, v[132:133]
	v_mul_f32_e32 v52, v53, v56
	v_or_b32_e32 v64, v70, v60
	v_mov_b64_e32 v[72:73], s[48:49]
	v_mul_f32_e32 v2, v57, v56
	v_mad_u64_u32 v[74:75], s[12:13], v64, s69, v[72:73]
	v_mad_i32_i24 v75, v71, s69, v75
	v_mov_b32_e32 v137, v3
	v_lshl_add_u64 v[70:71], v[74:75], 0, v[136:137]
	s_waitcnt vmcnt(0) lgkmcnt(0)
	v_mul_f32_e32 v64, v52, v69
	v_fma_f32 v64, v2, v68, -v64
	v_mul_f32_e32 v2, v2, v69
	v_fmac_f32_e32 v2, v52, v68
	v_cvt_pk_bf16_f32 v64, v64, s0
	v_cvt_pk_bf16_f32 v2, v2, s0
	global_store_short v[70:71], v64, off offset:256
	global_store_short v[70:71], v2, off offset:320
	v_lshlrev_b64 v[70:71], 12, v[138:139]
	v_mul_f32_e32 v52, v65, v56
	v_or_b32_e32 v64, v70, v60
	v_mul_f32_e32 v2, v61, v56
	v_mad_u64_u32 v[72:73], s[12:13], v64, s69, v[72:73]
	v_mul_f32_e32 v64, v52, v69
	v_fma_f32 v64, v2, v68, -v64
	v_mul_f32_e32 v2, v2, v69
	v_mad_i32_i24 v73, v71, s69, v73
	v_fmac_f32_e32 v2, v52, v68
	v_cvt_pk_bf16_f32 v64, v64, s0
	v_lshl_add_u64 v[70:71], v[72:73], 0, v[136:137]
	v_cvt_pk_bf16_f32 v2, v2, s0
	s_mov_b64 s[12:13], 0
	global_store_short v[70:71], v64, off offset:256
	global_store_short v[70:71], v2, off offset:320

; #define GAS __attribute__((address_space(1)))
; __device__ __forceinline__ unsigned cvtpk(float lo, float hi) { return __builtin_bit_cast(unsigned, __builtin_convertvector(f32x2_cv{lo, hi}, bf16x2_cv)); }
; __device__ __forceinline__ bf16_t f2bf(float f) { return (bf16_t)(cvtpk(f, 0.f) & 0xffffu); }
;     __device__ __forceinline__ void operator()(const f32x4 (&acc)[2][2][4][2], int brow, int bcol, int wr, int wc, int fr, int fq) const {
;     ...
;                     const float rs = rstd_from_ssq(ssq, row);
;                     if (bcol < 1024) {
; #pragma unroll
;                         for (int bj = 0; bj < 2; ++bj)
;                             *(GAS unsigned*)(qm + ((size_t)(b * 8 + (bcol >> 7) + bj) * S + sq) * 192 + wc * 32 + 2 * fr) = cvtpk(acc[ai][bj][m][0][j] * rs, acc[ai][bj][m][1][j] * rs);
;                     } else {
;                         const int i = (wc & 1) * 16 + fr;
;                         const float2 cs = r64[sq * 32 + i];
; #pragma unroll
;                         for (int bj = 0; bj < 2; ++bj) {
;                             const int head = ((bcol - 1024) >> 8) * 4 + bj * 2 + (wc >> 1);
;                             const float x1 = acc[ai][bj][m][0][j] * rs, x2 = acc[ai][bj][m][1][j] * rs;
;                             GAS bf16_t* p = (GAS bf16_t*)(qm + ((size_t)(b * 8 + head) * S + sq) * 192 + 128);
;                             p[i] = f2bf(x1 * cs.x - x2 * cs.y); p[32 + i] = f2bf(x2 * cs.x + x1 * cs.y);
;                         }
.LBB0_823:
	v_add_u32_e32 v56, 0x82, v134
	v_and_b32_e32 v53, 0xfce, v56
	s_mov_b64 s[12:13], -1
	v_mov_b32_e32 v52, v171
	s_and_b64 vcc, exec, s[42:43]
	s_cbranch_vccnz .LBB0_825
	v_lshl_or_b32 v2, v53, 8, v1
	v_lshl_add_u64 v[56:57], s[50:51], 0, v[2:3]
	flat_load_dwordx2 v[56:57], v[56:57]
	v_lshlrev_b64 v[60:61], 12, v[132:133]
	v_mul_f32_e32 v70, v54, v52
	v_or_b32_e32 v60, v60, v53
	v_mov_b64_e32 v[64:65], s[48:49]
	v_mul_f32_e32 v2, v58, v52
	v_mad_u64_u32 v[68:69], s[12:13], v60, s69, v[64:65]
	v_mad_i32_i24 v69, v61, s69, v69
	v_mov_b32_e32 v137, v3
	s_waitcnt vmcnt(0) lgkmcnt(0)
	v_mul_f32_e32 v60, v70, v57
	v_fma_f32 v60, v2, v56, -v60
	v_mul_f32_e32 v2, v2, v57
	v_fmac_f32_e32 v2, v70, v56
	v_cvt_pk_bf16_f32 v71, v60, s0
	v_lshl_add_u64 v[60:61], v[68:69], 0, v[136:137]
	v_cvt_pk_bf16_f32 v2, v2, s0
	global_store_short v[60:61], v71, off offset:256
	global_store_short v[60:61], v2, off offset:320
	v_lshlrev_b64 v[60:61], 12, v[138:139]
	v_mul_f32_e32 v68, v66, v52
	v_or_b32_e32 v60, v60, v53
	v_mul_f32_e32 v2, v62, v52
	v_mad_u64_u32 v[64:65], s[12:13], v60, s69, v[64:65]
	v_mul_f32_e32 v60, v68, v57
	v_fma_f32 v60, v2, v56, -v60
	v_mul_f32_e32 v2, v2, v57
	v_mad_i32_i24 v65, v61, s69, v65
	v_fmac_f32_e32 v2, v68, v56
	v_cvt_pk_bf16_f32 v69, v60, s0
	v_lshl_add_u64 v[60:61], v[64:65], 0, v[136:137]
	v_cvt_pk_bf16_f32 v2, v2, s0
	s_mov_b64 s[12:13], 0
	global_store_short v[60:61], v69, off offset:256
	global_store_short v[60:61], v2, off offset:320

; #define GAS __attribute__((address_space(1)))
; __device__ __forceinline__ unsigned cvtpk(float lo, float hi) { return __builtin_bit_cast(unsigned, __builtin_convertvector(f32x2_cv{lo, hi}, bf16x2_cv)); }
; __device__ __forceinline__ bf16_t f2bf(float f) { return (bf16_t)(cvtpk(f, 0.f) & 0xffffu); }
;     __device__ __forceinline__ void operator()(const f32x4 (&acc)[2][2][4][2], int brow, int bcol, int wr, int wc, int fr, int fq) const {
;     ...
;                     const float rs = rstd_from_ssq(ssq, row);
;                     if (bcol < 1024) {
; #pragma unroll
;                         for (int bj = 0; bj < 2; ++bj)
;                             *(GAS unsigned*)(qm + ((size_t)(b * 8 + (bcol >> 7) + bj) * S + sq) * 192 + wc * 32 + 2 * fr) = cvtpk(acc[ai][bj][m][0][j] * rs, acc[ai][bj][m][1][j] * rs);
;                     } else {
;                         const int i = (wc & 1) * 16 + fr;
;                         const float2 cs = r64[sq * 32 + i];
; #pragma unroll
;                         for (int bj = 0; bj < 2; ++bj) {
;                             const int head = ((bcol - 1024) >> 8) * 4 + bj * 2 + (wc >> 1);
;                             const float x1 = acc[ai][bj][m][0][j] * rs, x2 = acc[ai][bj][m][1][j] * rs;
;                             GAS bf16_t* p = (GAS bf16_t*)(qm + ((size_t)(b * 8 + head) * S + sq) * 192 + 128);
;                             p[i] = f2bf(x1 * cs.x - x2 * cs.y); p[32 + i] = f2bf(x2 * cs.x + x1 * cs.y);
;                         }
.LBB0_827:
	v_add_u32_e32 v56, 0x83, v134
	v_and_b32_e32 v53, 0xfcf, v56
	s_mov_b64 s[12:13], -1
	v_mov_b32_e32 v52, v172
	s_and_b64 vcc, exec, s[42:43]
	s_cbranch_vccnz .LBB0_829
	v_lshl_or_b32 v2, v53, 8, v1
	v_lshl_add_u64 v[56:57], s[50:51], 0, v[2:3]
	flat_load_dwordx2 v[56:57], v[56:57]
	v_lshlrev_b64 v[60:61], 12, v[132:133]
	v_mul_f32_e32 v54, v55, v52
	v_or_b32_e32 v58, v60, v53
	v_mov_b64_e32 v[64:65], s[48:49]
	v_mul_f32_e32 v2, v59, v52
	v_mad_u64_u32 v[68:69], s[12:13], v58, s69, v[64:65]
	v_mad_i32_i24 v69, v61, s69, v69
	v_mov_b32_e32 v137, v3
	v_lshl_add_u64 v[60:61], v[68:69], 0, v[136:137]
	s_waitcnt vmcnt(0) lgkmcnt(0)
	v_mul_f32_e32 v58, v54, v57
	v_fma_f32 v58, v2, v56, -v58
	v_mul_f32_e32 v2, v2, v57
	v_fmac_f32_e32 v2, v54, v56
	v_cvt_pk_bf16_f32 v58, v58, s0
	v_cvt_pk_bf16_f32 v2, v2, s0
	global_store_short v[60:61], v58, off offset:256
	global_store_short v[60:61], v2, off offset:320
	v_lshlrev_b64 v[60:61], 12, v[138:139]
	v_mul_f32_e32 v54, v67, v52
	v_or_b32_e32 v58, v60, v53
	v_mul_f32_e32 v2, v63, v52
	v_mad_u64_u32 v[64:65], s[12:13], v58, s69, v[64:65]
	v_mul_f32_e32 v58, v54, v57
	v_fma_f32 v58, v2, v56, -v58
	v_mul_f32_e32 v2, v2, v57
	v_mad_i32_i24 v65, v61, s69, v65
	v_fmac_f32_e32 v2, v54, v56
	v_cvt_pk_bf16_f32 v58, v58, s0
	v_lshl_add_u64 v[60:61], v[64:65], 0, v[136:137]
	v_cvt_pk_bf16_f32 v2, v2, s0
	s_mov_b64 s[12:13], 0
	global_store_short v[60:61], v58, off offset:256
	global_store_short v[60:61], v2, off offset:320

; #define GAS __attribute__((address_space(1)))
; __device__ __forceinline__ unsigned cvtpk(float lo, float hi) { return __builtin_bit_cast(unsigned, __builtin_convertvector(f32x2_cv{lo, hi}, bf16x2_cv)); }
; __device__ __forceinline__ bf16_t f2bf(float f) { return (bf16_t)(cvtpk(f, 0.f) & 0xffffu); }
;     __device__ __forceinline__ void operator()(const f32x4 (&acc)[2][2][4][2], int brow, int bcol, int wr, int wc, int fr, int fq) const {
;     ...
;                     const float rs = rstd_from_ssq(ssq, row);
;                     if (bcol < 1024) {
; #pragma unroll
;                         for (int bj = 0; bj < 2; ++bj)
;                             *(GAS unsigned*)(qm + ((size_t)(b * 8 + (bcol >> 7) + bj) * S + sq) * 192 + wc * 32 + 2 * fr) = cvtpk(acc[ai][bj][m][0][j] * rs, acc[ai][bj][m][1][j] * rs);
;                     } else {
;                         const int i = (wc & 1) * 16 + fr;
;                         const float2 cs = r64[sq * 32 + i];
; #pragma unroll
;                         for (int bj = 0; bj < 2; ++bj) {
;                             const int head = ((bcol - 1024) >> 8) * 4 + bj * 2 + (wc >> 1);
;                             const float x1 = acc[ai][bj][m][0][j] * rs, x2 = acc[ai][bj][m][1][j] * rs;
;                             GAS bf16_t* p = (GAS bf16_t*)(qm + ((size_t)(b * 8 + head) * S + sq) * 192 + 128);
;                             p[i] = f2bf(x1 * cs.x - x2 * cs.y); p[32 + i] = f2bf(x2 * cs.x + x1 * cs.y);
;                         }
.LBB0_831:
	v_add_u32_e32 v54, 0x90, v134
	v_and_b32_e32 v53, 0xfdc, v54
	s_mov_b64 s[12:13], -1
	v_mov_b32_e32 v52, v173
	s_and_b64 vcc, exec, s[42:43]
	s_cbranch_vccnz .LBB0_833
	v_lshl_or_b32 v2, v53, 8, v1
	v_lshl_add_u64 v[54:55], s[50:51], 0, v[2:3]
	flat_load_dwordx2 v[54:55], v[54:55]
	v_lshlrev_b64 v[56:57], 12, v[132:133]
	v_mul_f32_e32 v62, v36, v52
	v_or_b32_e32 v56, v56, v53
	v_mov_b64_e32 v[58:59], s[48:49]
	v_mul_f32_e32 v2, v40, v52
	v_mad_u64_u32 v[60:61], s[12:13], v56, s69, v[58:59]
	v_mad_i32_i24 v61, v57, s69, v61
	v_mov_b32_e32 v137, v3
	s_waitcnt vmcnt(0) lgkmcnt(0)
	v_mul_f32_e32 v56, v62, v55
	v_fma_f32 v56, v2, v54, -v56
	v_mul_f32_e32 v2, v2, v55
	v_fmac_f32_e32 v2, v62, v54
	v_cvt_pk_bf16_f32 v63, v56, s0
	v_lshl_add_u64 v[56:57], v[60:61], 0, v[136:137]
	v_cvt_pk_bf16_f32 v2, v2, s0
	global_store_short v[56:57], v63, off offset:256
	global_store_short v[56:57], v2, off offset:320
	v_lshlrev_b64 v[56:57], 12, v[138:139]
	v_mul_f32_e32 v60, v48, v52
	v_or_b32_e32 v56, v56, v53
	v_mul_f32_e32 v2, v44, v52
	v_mad_u64_u32 v[58:59], s[12:13], v56, s69, v[58:59]
	v_mul_f32_e32 v56, v60, v55
	v_fma_f32 v56, v2, v54, -v56
	v_mul_f32_e32 v2, v2, v55
	v_mad_i32_i24 v59, v57, s69, v59
	v_fmac_f32_e32 v2, v60, v54
	v_cvt_pk_bf16_f32 v61, v56, s0
	v_lshl_add_u64 v[56:57], v[58:59], 0, v[136:137]
	v_cvt_pk_bf16_f32 v2, v2, s0
	s_mov_b64 s[12:13], 0
	global_store_short v[56:57], v61, off offset:256
	global_store_short v[56:57], v2, off offset:320

; #define GAS __attribute__((address_space(1)))
; __device__ __forceinline__ unsigned cvtpk(float lo, float hi) { return __builtin_bit_cast(unsigned, __builtin_convertvector(f32x2_cv{lo, hi}, bf16x2_cv)); }
; __device__ __forceinline__ bf16_t f2bf(float f) { return (bf16_t)(cvtpk(f, 0.f) & 0xffffu); }
;     __device__ __forceinline__ void operator()(const f32x4 (&acc)[2][2][4][2], int brow, int bcol, int wr, int wc, int fr, int fq) const {
;     ...
;                     const float rs = rstd_from_ssq(ssq, row);
;                     if (bcol < 1024) {
; #pragma unroll
;                         for (int bj = 0; bj < 2; ++bj)
;                             *(GAS unsigned*)(qm + ((size_t)(b * 8 + (bcol >> 7) + bj) * S + sq) * 192 + wc * 32 + 2 * fr) = cvtpk(acc[ai][bj][m][0][j] * rs, acc[ai][bj][m][1][j] * rs);
;                     } else {
;                         const int i = (wc & 1) * 16 + fr;
;                         const float2 cs = r64[sq * 32 + i];
; #pragma unroll
;                         for (int bj = 0; bj < 2; ++bj) {
;                             const int head = ((bcol - 1024) >> 8) * 4 + bj * 2 + (wc >> 1);
;                             const float x1 = acc[ai][bj][m][0][j] * rs, x2 = acc[ai][bj][m][1][j] * rs;
;                             GAS bf16_t* p = (GAS bf16_t*)(qm + ((size_t)(b * 8 + head) * S + sq) * 192 + 128);
;                             p[i] = f2bf(x1 * cs.x - x2 * cs.y); p[32 + i] = f2bf(x2 * cs.x + x1 * cs.y);
;                         }
.LBB0_835:
	v_add_u32_e32 v52, 0x91, v134
	v_and_b32_e32 v44, 0xfdd, v52
	s_mov_b64 s[12:13], -1
	v_mov_b32_e32 v40, v174
	s_and_b64 vcc, exec, s[42:43]
	s_cbranch_vccnz .LBB0_837
	v_lshl_or_b32 v2, v44, 8, v1
	v_lshl_add_u64 v[52:53], s[50:51], 0, v[2:3]
	flat_load_dwordx2 v[52:53], v[52:53]
	v_lshlrev_b64 v[54:55], 12, v[132:133]
	v_mul_f32_e32 v36, v37, v40
	v_or_b32_e32 v48, v54, v44
	v_mov_b64_e32 v[56:57], s[48:49]
	v_mul_f32_e32 v2, v41, v40
	v_mad_u64_u32 v[58:59], s[12:13], v48, s69, v[56:57]
	v_mad_i32_i24 v59, v55, s69, v59
	v_mov_b32_e32 v137, v3
	v_lshl_add_u64 v[54:55], v[58:59], 0, v[136:137]
	s_waitcnt vmcnt(0) lgkmcnt(0)
	v_mul_f32_e32 v48, v36, v53
	v_fma_f32 v48, v2, v52, -v48
	v_mul_f32_e32 v2, v2, v53
	v_fmac_f32_e32 v2, v36, v52
	v_cvt_pk_bf16_f32 v48, v48, s0
	v_cvt_pk_bf16_f32 v2, v2, s0
	global_store_short v[54:55], v48, off offset:256
	global_store_short v[54:55], v2, off offset:320
	v_lshlrev_b64 v[54:55], 12, v[138:139]
	v_mul_f32_e32 v36, v49, v40
	v_or_b32_e32 v48, v54, v44
	v_mul_f32_e32 v2, v45, v40
	v_mad_u64_u32 v[56:57], s[12:13], v48, s69, v[56:57]
	v_mul_f32_e32 v48, v36, v53
	v_fma_f32 v48, v2, v52, -v48
	v_mul_f32_e32 v2, v2, v53
	v_mad_i32_i24 v57, v55, s69, v57
	v_fmac_f32_e32 v2, v36, v52
	v_cvt_pk_bf16_f32 v48, v48, s0
	v_lshl_add_u64 v[54:55], v[56:57], 0, v[136:137]
	v_cvt_pk_bf16_f32 v2, v2, s0
	s_mov_b64 s[12:13], 0
	global_store_short v[54:55], v48, off offset:256
	global_store_short v[54:55], v2, off offset:320

; #define GAS __attribute__((address_space(1)))
; __device__ __forceinline__ unsigned cvtpk(float lo, float hi) { return __builtin_bit_cast(unsigned, __builtin_convertvector(f32x2_cv{lo, hi}, bf16x2_cv)); }
; __device__ __forceinline__ bf16_t f2bf(float f) { return (bf16_t)(cvtpk(f, 0.f) & 0xffffu); }
;     __device__ __forceinline__ void operator()(const f32x4 (&acc)[2][2][4][2], int brow, int bcol, int wr, int wc, int fr, int fq) const {
;     ...
;                     const float rs = rstd_from_ssq(ssq, row);
;                     if (bcol < 1024) {
; #pragma unroll
;                         for (int bj = 0; bj < 2; ++bj)
;                             *(GAS unsigned*)(qm + ((size_t)(b * 8 + (bcol >> 7) + bj) * S + sq) * 192 + wc * 32 + 2 * fr) = cvtpk(acc[ai][bj][m][0][j] * rs, acc[ai][bj][m][1][j] * rs);
;                     } else {
;                         const int i = (wc & 1) * 16 + fr;
;                         const float2 cs = r64[sq * 32 + i];
; #pragma unroll
;                         for (int bj = 0; bj < 2; ++bj) {
;                             const int head = ((bcol - 1024) >> 8) * 4 + bj * 2 + (wc >> 1);
;                             const float x1 = acc[ai][bj][m][0][j] * rs, x2 = acc[ai][bj][m][1][j] * rs;
;                             GAS bf16_t* p = (GAS bf16_t*)(qm + ((size_t)(b * 8 + head) * S + sq) * 192 + 128);
;                             p[i] = f2bf(x1 * cs.x - x2 * cs.y); p[32 + i] = f2bf(x2 * cs.x + x1 * cs.y);
;                         }
.LBB0_839:
	v_add_u32_e32 v40, 0x92, v134
	v_and_b32_e32 v37, 0xfde, v40
	s_mov_b64 s[12:13], -1
	v_mov_b32_e32 v36, v175
	s_and_b64 vcc, exec, s[42:43]
	s_cbranch_vccnz .LBB0_841
	v_lshl_or_b32 v2, v37, 8, v1
	v_lshl_add_u64 v[40:41], s[50:51], 0, v[2:3]
	flat_load_dwordx2 v[40:41], v[40:41]
	v_lshlrev_b64 v[44:45], 12, v[132:133]
	v_mul_f32_e32 v54, v38, v36
	v_or_b32_e32 v44, v44, v37
	v_mov_b64_e32 v[48:49], s[48:49]
	v_mul_f32_e32 v2, v42, v36
	v_mad_u64_u32 v[52:53], s[12:13], v44, s69, v[48:49]
	v_mad_i32_i24 v53, v45, s69, v53
	v_mov_b32_e32 v137, v3
	s_waitcnt vmcnt(0) lgkmcnt(0)
	v_mul_f32_e32 v44, v54, v41
	v_fma_f32 v44, v2, v40, -v44
	v_mul_f32_e32 v2, v2, v41
	v_fmac_f32_e32 v2, v54, v40
	v_cvt_pk_bf16_f32 v55, v44, s0
	v_lshl_add_u64 v[44:45], v[52:53], 0, v[136:137]
	v_cvt_pk_bf16_f32 v2, v2, s0
	global_store_short v[44:45], v55, off offset:256
	global_store_short v[44:45], v2, off offset:320
	v_lshlrev_b64 v[44:45], 12, v[138:139]
	v_mul_f32_e32 v52, v50, v36
	v_or_b32_e32 v44, v44, v37
	v_mul_f32_e32 v2, v46, v36
	v_mad_u64_u32 v[48:49], s[12:13], v44, s69, v[48:49]
	v_mul_f32_e32 v44, v52, v41
	v_fma_f32 v44, v2, v40, -v44
	v_mul_f32_e32 v2, v2, v41
	v_mad_i32_i24 v49, v45, s69, v49
	v_fmac_f32_e32 v2, v52, v40
	v_cvt_pk_bf16_f32 v53, v44, s0
	v_lshl_add_u64 v[44:45], v[48:49], 0, v[136:137]
	v_cvt_pk_bf16_f32 v2, v2, s0
	s_mov_b64 s[12:13], 0
	global_store_short v[44:45], v53, off offset:256
	global_store_short v[44:45], v2, off offset:320

; #define GAS __attribute__((address_space(1)))
; __device__ __forceinline__ unsigned cvtpk(float lo, float hi) { return __builtin_bit_cast(unsigned, __builtin_convertvector(f32x2_cv{lo, hi}, bf16x2_cv)); }
; __device__ __forceinline__ bf16_t f2bf(float f) { return (bf16_t)(cvtpk(f, 0.f) & 0xffffu); }
;     __device__ __forceinline__ void operator()(const f32x4 (&acc)[2][2][4][2], int brow, int bcol, int wr, int wc, int fr, int fq) const {
;     ...
;                     const float rs = rstd_from_ssq(ssq, row);
;                     if (bcol < 1024) {
; #pragma unroll
;                         for (int bj = 0; bj < 2; ++bj)
;                             *(GAS unsigned*)(qm + ((size_t)(b * 8 + (bcol >> 7) + bj) * S + sq) * 192 + wc * 32 + 2 * fr) = cvtpk(acc[ai][bj][m][0][j] * rs, acc[ai][bj][m][1][j] * rs);
;                     } else {
;                         const int i = (wc & 1) * 16 + fr;
;                         const float2 cs = r64[sq * 32 + i];
; #pragma unroll
;                         for (int bj = 0; bj < 2; ++bj) {
;                             const int head = ((bcol - 1024) >> 8) * 4 + bj * 2 + (wc >> 1);
;                             const float x1 = acc[ai][bj][m][0][j] * rs, x2 = acc[ai][bj][m][1][j] * rs;
;                             GAS bf16_t* p = (GAS bf16_t*)(qm + ((size_t)(b * 8 + head) * S + sq) * 192 + 128);
;                             p[i] = f2bf(x1 * cs.x - x2 * cs.y); p[32 + i] = f2bf(x2 * cs.x + x1 * cs.y);
;                         }
.LBB0_843:
	v_add_u32_e32 v40, 0x93, v134
	v_and_b32_e32 v37, 0xfdf, v40
	s_mov_b64 s[12:13], -1
	v_mov_b32_e32 v36, v176
	s_and_b64 vcc, exec, s[42:43]
	s_cbranch_vccnz .LBB0_845
	v_lshl_or_b32 v2, v37, 8, v1
	v_lshl_add_u64 v[40:41], s[50:51], 0, v[2:3]
	flat_load_dwordx2 v[40:41], v[40:41]
	v_lshlrev_b64 v[44:45], 12, v[132:133]
	v_mul_f32_e32 v38, v39, v36
	v_or_b32_e32 v42, v44, v37
	v_mov_b64_e32 v[48:49], s[48:49]
	v_mul_f32_e32 v2, v43, v36
	v_mad_u64_u32 v[52:53], s[12:13], v42, s69, v[48:49]
	v_mad_i32_i24 v53, v45, s69, v53
	v_mov_b32_e32 v137, v3
	v_lshl_add_u64 v[44:45], v[52:53], 0, v[136:137]
	s_waitcnt vmcnt(0) lgkmcnt(0)
	v_mul_f32_e32 v42, v38, v41
	v_fma_f32 v42, v2, v40, -v42
	v_mul_f32_e32 v2, v2, v41
	v_fmac_f32_e32 v2, v38, v40
	v_cvt_pk_bf16_f32 v42, v42, s0
	v_cvt_pk_bf16_f32 v2, v2, s0
	global_store_short v[44:45], v42, off offset:256
	global_store_short v[44:45], v2, off offset:320
	v_lshlrev_b64 v[44:45], 12, v[138:139]
	v_mul_f32_e32 v38, v51, v36
	v_or_b32_e32 v42, v44, v37
	v_mul_f32_e32 v2, v47, v36
	v_mad_u64_u32 v[48:49], s[12:13], v42, s69, v[48:49]
	v_mul_f32_e32 v42, v38, v41
	v_fma_f32 v42, v2, v40, -v42
	v_mul_f32_e32 v2, v2, v41
	v_mad_i32_i24 v49, v45, s69, v49
	v_fmac_f32_e32 v2, v38, v40
	v_cvt_pk_bf16_f32 v42, v42, s0
	v_lshl_add_u64 v[44:45], v[48:49], 0, v[136:137]
	v_cvt_pk_bf16_f32 v2, v2, s0
	s_mov_b64 s[12:13], 0
	global_store_short v[44:45], v42, off offset:256
	global_store_short v[44:45], v2, off offset:320

; #define GAS __attribute__((address_space(1)))
; __device__ __forceinline__ unsigned cvtpk(float lo, float hi) { return __builtin_bit_cast(unsigned, __builtin_convertvector(f32x2_cv{lo, hi}, bf16x2_cv)); }
; __device__ __forceinline__ bf16_t f2bf(float f) { return (bf16_t)(cvtpk(f, 0.f) & 0xffffu); }
;     __device__ __forceinline__ void operator()(const f32x4 (&acc)[2][2][4][2], int brow, int bcol, int wr, int wc, int fr, int fq) const {
;     ...
;                     const float rs = rstd_from_ssq(ssq, row);
;                     if (bcol < 1024) {
; #pragma unroll
;                         for (int bj = 0; bj < 2; ++bj)
;                             *(GAS unsigned*)(qm + ((size_t)(b * 8 + (bcol >> 7) + bj) * S + sq) * 192 + wc * 32 + 2 * fr) = cvtpk(acc[ai][bj][m][0][j] * rs, acc[ai][bj][m][1][j] * rs);
;                     } else {
;                         const int i = (wc & 1) * 16 + fr;
;                         const float2 cs = r64[sq * 32 + i];
; #pragma unroll
;                         for (int bj = 0; bj < 2; ++bj) {
;                             const int head = ((bcol - 1024) >> 8) * 4 + bj * 2 + (wc >> 1);
;                             const float x1 = acc[ai][bj][m][0][j] * rs, x2 = acc[ai][bj][m][1][j] * rs;
;                             GAS bf16_t* p = (GAS bf16_t*)(qm + ((size_t)(b * 8 + head) * S + sq) * 192 + 128);
;                             p[i] = f2bf(x1 * cs.x - x2 * cs.y); p[32 + i] = f2bf(x2 * cs.x + x1 * cs.y);
;                         }
.LBB0_847:
	v_add_u32_e32 v38, 0xa0, v134
	v_and_b32_e32 v37, 0xfec, v38
	s_mov_b64 s[12:13], -1
	v_mov_b32_e32 v36, v177
	s_and_b64 vcc, exec, s[42:43]
	s_cbranch_vccnz .LBB0_849
	v_lshl_or_b32 v2, v37, 8, v1
	v_lshl_add_u64 v[38:39], s[50:51], 0, v[2:3]
	flat_load_dwordx2 v[38:39], v[38:39]
	v_lshlrev_b64 v[40:41], 12, v[132:133]
	v_mul_f32_e32 v46, v20, v36
	v_or_b32_e32 v40, v40, v37
	v_mov_b64_e32 v[42:43], s[48:49]
	v_mul_f32_e32 v2, v24, v36
	v_mad_u64_u32 v[44:45], s[12:13], v40, s69, v[42:43]
	v_mad_i32_i24 v45, v41, s69, v45
	v_mov_b32_e32 v137, v3
	s_waitcnt vmcnt(0) lgkmcnt(0)
	v_mul_f32_e32 v40, v46, v39
	v_fma_f32 v40, v2, v38, -v40
	v_mul_f32_e32 v2, v2, v39
	v_fmac_f32_e32 v2, v46, v38
	v_cvt_pk_bf16_f32 v47, v40, s0
	v_lshl_add_u64 v[40:41], v[44:45], 0, v[136:137]
	v_cvt_pk_bf16_f32 v2, v2, s0
	global_store_short v[40:41], v47, off offset:256
	global_store_short v[40:41], v2, off offset:320
	v_lshlrev_b64 v[40:41], 12, v[138:139]
	v_mul_f32_e32 v44, v32, v36
	v_or_b32_e32 v40, v40, v37
	v_mul_f32_e32 v2, v28, v36
	v_mad_u64_u32 v[42:43], s[12:13], v40, s69, v[42:43]
	v_mul_f32_e32 v40, v44, v39
	v_fma_f32 v40, v2, v38, -v40
	v_mul_f32_e32 v2, v2, v39
	v_mad_i32_i24 v43, v41, s69, v43
	v_fmac_f32_e32 v2, v44, v38
	v_cvt_pk_bf16_f32 v45, v40, s0
	v_lshl_add_u64 v[40:41], v[42:43], 0, v[136:137]
	v_cvt_pk_bf16_f32 v2, v2, s0
	s_mov_b64 s[12:13], 0
	global_store_short v[40:41], v45, off offset:256
	global_store_short v[40:41], v2, off offset:320

; #define GAS __attribute__((address_space(1)))
; __device__ __forceinline__ unsigned cvtpk(float lo, float hi) { return __builtin_bit_cast(unsigned, __builtin_convertvector(f32x2_cv{lo, hi}, bf16x2_cv)); }
; __device__ __forceinline__ bf16_t f2bf(float f) { return (bf16_t)(cvtpk(f, 0.f) & 0xffffu); }
;     __device__ __forceinline__ void operator()(const f32x4 (&acc)[2][2][4][2], int brow, int bcol, int wr, int wc, int fr, int fq) const {
;     ...
;                     const float rs = rstd_from_ssq(ssq, row);
;                     if (bcol < 1024) {
; #pragma unroll
;                         for (int bj = 0; bj < 2; ++bj)
;                             *(GAS unsigned*)(qm + ((size_t)(b * 8 + (bcol >> 7) + bj) * S + sq) * 192 + wc * 32 + 2 * fr) = cvtpk(acc[ai][bj][m][0][j] * rs, acc[ai][bj][m][1][j] * rs);
;                     } else {
;                         const int i = (wc & 1) * 16 + fr;
;                         const float2 cs = r64[sq * 32 + i];
; #pragma unroll
;                         for (int bj = 0; bj < 2; ++bj) {
;                             const int head = ((bcol - 1024) >> 8) * 4 + bj * 2 + (wc >> 1);
;                             const float x1 = acc[ai][bj][m][0][j] * rs, x2 = acc[ai][bj][m][1][j] * rs;
;                             GAS bf16_t* p = (GAS bf16_t*)(qm + ((size_t)(b * 8 + head) * S + sq) * 192 + 128);
;                             p[i] = f2bf(x1 * cs.x - x2 * cs.y); p[32 + i] = f2bf(x2 * cs.x + x1 * cs.y);
;                         }
.LBB0_851:
	v_add_u32_e32 v36, 0xa1, v134
	v_and_b32_e32 v28, 0xfed, v36
	s_mov_b64 s[12:13], -1
	v_mov_b32_e32 v24, v178
	s_and_b64 vcc, exec, s[42:43]
	s_cbranch_vccnz .LBB0_853
	v_lshl_or_b32 v2, v28, 8, v1
	v_lshl_add_u64 v[36:37], s[50:51], 0, v[2:3]
	flat_load_dwordx2 v[36:37], v[36:37]
	v_lshlrev_b64 v[38:39], 12, v[132:133]
	v_mul_f32_e32 v20, v21, v24
	v_or_b32_e32 v32, v38, v28
	v_mov_b64_e32 v[40:41], s[48:49]
	v_mul_f32_e32 v2, v25, v24
	v_mad_u64_u32 v[42:43], s[12:13], v32, s69, v[40:41]
	v_mad_i32_i24 v43, v39, s69, v43
	v_mov_b32_e32 v137, v3
	v_lshl_add_u64 v[38:39], v[42:43], 0, v[136:137]
	s_waitcnt vmcnt(0) lgkmcnt(0)
	v_mul_f32_e32 v32, v20, v37
	v_fma_f32 v32, v2, v36, -v32
	v_mul_f32_e32 v2, v2, v37
	v_fmac_f32_e32 v2, v20, v36
	v_cvt_pk_bf16_f32 v32, v32, s0
	v_cvt_pk_bf16_f32 v2, v2, s0
	global_store_short v[38:39], v32, off offset:256
	global_store_short v[38:39], v2, off offset:320
	v_lshlrev_b64 v[38:39], 12, v[138:139]
	v_mul_f32_e32 v20, v33, v24
	v_or_b32_e32 v32, v38, v28
	v_mul_f32_e32 v2, v29, v24
	v_mad_u64_u32 v[40:41], s[12:13], v32, s69, v[40:41]
	v_mul_f32_e32 v32, v20, v37
	v_fma_f32 v32, v2, v36, -v32
	v_mul_f32_e32 v2, v2, v37
	v_mad_i32_i24 v41, v39, s69, v41
	v_fmac_f32_e32 v2, v20, v36
	v_cvt_pk_bf16_f32 v32, v32, s0
	v_lshl_add_u64 v[38:39], v[40:41], 0, v[136:137]
	v_cvt_pk_bf16_f32 v2, v2, s0
	s_mov_b64 s[12:13], 0
	global_store_short v[38:39], v32, off offset:256
	global_store_short v[38:39], v2, off offset:320

; #define GAS __attribute__((address_space(1)))
; __device__ __forceinline__ unsigned cvtpk(float lo, float hi) { return __builtin_bit_cast(unsigned, __builtin_convertvector(f32x2_cv{lo, hi}, bf16x2_cv)); }
; __device__ __forceinline__ bf16_t f2bf(float f) { return (bf16_t)(cvtpk(f, 0.f) & 0xffffu); }
;     __device__ __forceinline__ void operator()(const f32x4 (&acc)[2][2][4][2], int brow, int bcol, int wr, int wc, int fr, int fq) const {
;     ...
;                     const float rs = rstd_from_ssq(ssq, row);
;                     if (bcol < 1024) {
; #pragma unroll
;                         for (int bj = 0; bj < 2; ++bj)
;                             *(GAS unsigned*)(qm + ((size_t)(b * 8 + (bcol >> 7) + bj) * S + sq) * 192 + wc * 32 + 2 * fr) = cvtpk(acc[ai][bj][m][0][j] * rs, acc[ai][bj][m][1][j] * rs);
;                     } else {
;                         const int i = (wc & 1) * 16 + fr;
;                         const float2 cs = r64[sq * 32 + i];
; #pragma unroll
;                         for (int bj = 0; bj < 2; ++bj) {
;                             const int head = ((bcol - 1024) >> 8) * 4 + bj * 2 + (wc >> 1);
;                             const float x1 = acc[ai][bj][m][0][j] * rs, x2 = acc[ai][bj][m][1][j] * rs;
;                             GAS bf16_t* p = (GAS bf16_t*)(qm + ((size_t)(b * 8 + head) * S + sq) * 192 + 128);
;                             p[i] = f2bf(x1 * cs.x - x2 * cs.y); p[32 + i] = f2bf(x2 * cs.x + x1 * cs.y);
;                         }
.LBB0_855:
	v_add_u32_e32 v24, 0xa2, v134
	v_and_b32_e32 v21, 0xfee, v24
	s_mov_b64 s[12:13], -1
	v_mov_b32_e32 v20, v179
	s_and_b64 vcc, exec, s[42:43]
	s_cbranch_vccnz .LBB0_857
	v_lshl_or_b32 v2, v21, 8, v1
	v_lshl_add_u64 v[24:25], s[50:51], 0, v[2:3]
	flat_load_dwordx2 v[24:25], v[24:25]
	v_lshlrev_b64 v[28:29], 12, v[132:133]
	v_mul_f32_e32 v38, v22, v20
	v_or_b32_e32 v28, v28, v21
	v_mov_b64_e32 v[32:33], s[48:49]
	v_mul_f32_e32 v2, v26, v20
	v_mad_u64_u32 v[36:37], s[12:13], v28, s69, v[32:33]
	v_mad_i32_i24 v37, v29, s69, v37
	v_mov_b32_e32 v137, v3
	s_waitcnt vmcnt(0) lgkmcnt(0)
	v_mul_f32_e32 v28, v38, v25
	v_fma_f32 v28, v2, v24, -v28
	v_mul_f32_e32 v2, v2, v25
	v_fmac_f32_e32 v2, v38, v24
	v_cvt_pk_bf16_f32 v39, v28, s0
	v_lshl_add_u64 v[28:29], v[36:37], 0, v[136:137]
	v_cvt_pk_bf16_f32 v2, v2, s0
	global_store_short v[28:29], v39, off offset:256
	global_store_short v[28:29], v2, off offset:320
	v_lshlrev_b64 v[28:29], 12, v[138:139]
	v_mul_f32_e32 v36, v34, v20
	v_or_b32_e32 v28, v28, v21
	v_mul_f32_e32 v2, v30, v20
	v_mad_u64_u32 v[32:33], s[12:13], v28, s69, v[32:33]
	v_mul_f32_e32 v28, v36, v25
	v_fma_f32 v28, v2, v24, -v28
	v_mul_f32_e32 v2, v2, v25
	v_mad_i32_i24 v33, v29, s69, v33
	v_fmac_f32_e32 v2, v36, v24
	v_cvt_pk_bf16_f32 v37, v28, s0
	v_lshl_add_u64 v[28:29], v[32:33], 0, v[136:137]
	v_cvt_pk_bf16_f32 v2, v2, s0
	s_mov_b64 s[12:13], 0
	global_store_short v[28:29], v37, off offset:256
	global_store_short v[28:29], v2, off offset:320

; #define GAS __attribute__((address_space(1)))
; __device__ __forceinline__ unsigned cvtpk(float lo, float hi) { return __builtin_bit_cast(unsigned, __builtin_convertvector(f32x2_cv{lo, hi}, bf16x2_cv)); }
; __device__ __forceinline__ bf16_t f2bf(float f) { return (bf16_t)(cvtpk(f, 0.f) & 0xffffu); }
;     __device__ __forceinline__ void operator()(const f32x4 (&acc)[2][2][4][2], int brow, int bcol, int wr, int wc, int fr, int fq) const {
;     ...
;                     const float rs = rstd_from_ssq(ssq, row);
;                     if (bcol < 1024) {
; #pragma unroll
;                         for (int bj = 0; bj < 2; ++bj)
;                             *(GAS unsigned*)(qm + ((size_t)(b * 8 + (bcol >> 7) + bj) * S + sq) * 192 + wc * 32 + 2 * fr) = cvtpk(acc[ai][bj][m][0][j] * rs, acc[ai][bj][m][1][j] * rs);
;                     } else {
;                         const int i = (wc & 1) * 16 + fr;
;                         const float2 cs = r64[sq * 32 + i];
; #pragma unroll
;                         for (int bj = 0; bj < 2; ++bj) {
;                             const int head = ((bcol - 1024) >> 8) * 4 + bj * 2 + (wc >> 1);
;                             const float x1 = acc[ai][bj][m][0][j] * rs, x2 = acc[ai][bj][m][1][j] * rs;
;                             GAS bf16_t* p = (GAS bf16_t*)(qm + ((size_t)(b * 8 + head) * S + sq) * 192 + 128);
;                             p[i] = f2bf(x1 * cs.x - x2 * cs.y); p[32 + i] = f2bf(x2 * cs.x + x1 * cs.y);
;                         }
.LBB0_859:
	v_add_u32_e32 v24, 0xa3, v134
	v_and_b32_e32 v21, 0xfef, v24
	s_mov_b64 s[12:13], -1
	v_mov_b32_e32 v20, v180
	s_and_b64 vcc, exec, s[42:43]
	s_cbranch_vccnz .LBB0_861
	v_lshl_or_b32 v2, v21, 8, v1
	v_lshl_add_u64 v[24:25], s[50:51], 0, v[2:3]
	flat_load_dwordx2 v[24:25], v[24:25]
	v_lshlrev_b64 v[28:29], 12, v[132:133]
	v_mul_f32_e32 v22, v23, v20
	v_or_b32_e32 v26, v28, v21
	v_mov_b64_e32 v[32:33], s[48:49]
	v_mul_f32_e32 v2, v27, v20
	v_mad_u64_u32 v[36:37], s[12:13], v26, s69, v[32:33]
	v_mad_i32_i24 v37, v29, s69, v37
	v_mov_b32_e32 v137, v3
	v_lshl_add_u64 v[28:29], v[36:37], 0, v[136:137]
	s_waitcnt vmcnt(0) lgkmcnt(0)
	v_mul_f32_e32 v26, v22, v25
	v_fma_f32 v26, v2, v24, -v26
	v_mul_f32_e32 v2, v2, v25
	v_fmac_f32_e32 v2, v22, v24
	v_cvt_pk_bf16_f32 v26, v26, s0
	v_cvt_pk_bf16_f32 v2, v2, s0
	global_store_short v[28:29], v26, off offset:256
	global_store_short v[28:29], v2, off offset:320
	v_lshlrev_b64 v[28:29], 12, v[138:139]
	v_mul_f32_e32 v22, v35, v20
	v_or_b32_e32 v26, v28, v21
	v_mul_f32_e32 v2, v31, v20
	v_mad_u64_u32 v[32:33], s[12:13], v26, s69, v[32:33]
	v_mul_f32_e32 v26, v22, v25
	v_fma_f32 v26, v2, v24, -v26
	v_mul_f32_e32 v2, v2, v25
	v_mad_i32_i24 v33, v29, s69, v33
	v_fmac_f32_e32 v2, v22, v24
	v_cvt_pk_bf16_f32 v26, v26, s0
	v_lshl_add_u64 v[28:29], v[32:33], 0, v[136:137]
	v_cvt_pk_bf16_f32 v2, v2, s0
	s_mov_b64 s[12:13], 0
	global_store_short v[28:29], v26, off offset:256
	global_store_short v[28:29], v2, off offset:320

; #define GAS __attribute__((address_space(1)))
; __device__ __forceinline__ unsigned cvtpk(float lo, float hi) { return __builtin_bit_cast(unsigned, __builtin_convertvector(f32x2_cv{lo, hi}, bf16x2_cv)); }
; __device__ __forceinline__ bf16_t f2bf(float f) { return (bf16_t)(cvtpk(f, 0.f) & 0xffffu); }
;     __device__ __forceinline__ void operator()(const f32x4 (&acc)[2][2][4][2], int brow, int bcol, int wr, int wc, int fr, int fq) const {
;     ...
;                     const float rs = rstd_from_ssq(ssq, row);
;                     if (bcol < 1024) {
; #pragma unroll
;                         for (int bj = 0; bj < 2; ++bj)
;                             *(GAS unsigned*)(qm + ((size_t)(b * 8 + (bcol >> 7) + bj) * S + sq) * 192 + wc * 32 + 2 * fr) = cvtpk(acc[ai][bj][m][0][j] * rs, acc[ai][bj][m][1][j] * rs);
;                     } else {
;                         const int i = (wc & 1) * 16 + fr;
;                         const float2 cs = r64[sq * 32 + i];
; #pragma unroll
;                         for (int bj = 0; bj < 2; ++bj) {
;                             const int head = ((bcol - 1024) >> 8) * 4 + bj * 2 + (wc >> 1);
;                             const float x1 = acc[ai][bj][m][0][j] * rs, x2 = acc[ai][bj][m][1][j] * rs;
;                             GAS bf16_t* p = (GAS bf16_t*)(qm + ((size_t)(b * 8 + head) * S + sq) * 192 + 128);
;                             p[i] = f2bf(x1 * cs.x - x2 * cs.y); p[32 + i] = f2bf(x2 * cs.x + x1 * cs.y);
;                         }
.LBB0_863:
	v_add_u32_e32 v22, 0xb0, v134
	v_and_b32_e32 v21, 0xffc, v22
	s_mov_b64 s[12:13], -1
	v_mov_b32_e32 v20, v181
	s_and_b64 vcc, exec, s[42:43]
	s_cbranch_vccnz .LBB0_865
	v_lshl_or_b32 v2, v21, 8, v1
	v_lshl_add_u64 v[22:23], s[50:51], 0, v[2:3]
	flat_load_dwordx2 v[22:23], v[22:23]
	v_lshlrev_b64 v[24:25], 12, v[132:133]
	v_mul_f32_e32 v30, v4, v20
	v_or_b32_e32 v24, v24, v21
	v_mov_b64_e32 v[26:27], s[48:49]
	v_mul_f32_e32 v2, v8, v20
	v_mad_u64_u32 v[28:29], s[12:13], v24, s69, v[26:27]
	v_mad_i32_i24 v29, v25, s69, v29
	v_mov_b32_e32 v137, v3
	s_waitcnt vmcnt(0) lgkmcnt(0)
	v_mul_f32_e32 v24, v30, v23
	v_fma_f32 v24, v2, v22, -v24
	v_mul_f32_e32 v2, v2, v23
	v_fmac_f32_e32 v2, v30, v22
	v_cvt_pk_bf16_f32 v31, v24, s0
	v_lshl_add_u64 v[24:25], v[28:29], 0, v[136:137]
	v_cvt_pk_bf16_f32 v2, v2, s0
	global_store_short v[24:25], v31, off offset:256
	global_store_short v[24:25], v2, off offset:320
	v_lshlrev_b64 v[24:25], 12, v[138:139]
	v_mul_f32_e32 v28, v16, v20
	v_or_b32_e32 v24, v24, v21
	v_mul_f32_e32 v2, v12, v20
	v_mad_u64_u32 v[26:27], s[12:13], v24, s69, v[26:27]
	v_mul_f32_e32 v24, v28, v23
	v_fma_f32 v24, v2, v22, -v24
	v_mul_f32_e32 v2, v2, v23
	v_mad_i32_i24 v27, v25, s69, v27
	v_fmac_f32_e32 v2, v28, v22
	v_cvt_pk_bf16_f32 v29, v24, s0
	v_lshl_add_u64 v[24:25], v[26:27], 0, v[136:137]
	v_cvt_pk_bf16_f32 v2, v2, s0
	s_mov_b64 s[12:13], 0
	global_store_short v[24:25], v29, off offset:256
	global_store_short v[24:25], v2, off offset:320

; #define GAS __attribute__((address_space(1)))
; __device__ __forceinline__ unsigned cvtpk(float lo, float hi) { return __builtin_bit_cast(unsigned, __builtin_convertvector(f32x2_cv{lo, hi}, bf16x2_cv)); }
; __device__ __forceinline__ bf16_t f2bf(float f) { return (bf16_t)(cvtpk(f, 0.f) & 0xffffu); }
;     __device__ __forceinline__ void operator()(const f32x4 (&acc)[2][2][4][2], int brow, int bcol, int wr, int wc, int fr, int fq) const {
;     ...
;                     const float rs = rstd_from_ssq(ssq, row);
;                     if (bcol < 1024) {
; #pragma unroll
;                         for (int bj = 0; bj < 2; ++bj)
;                             *(GAS unsigned*)(qm + ((size_t)(b * 8 + (bcol >> 7) + bj) * S + sq) * 192 + wc * 32 + 2 * fr) = cvtpk(acc[ai][bj][m][0][j] * rs, acc[ai][bj][m][1][j] * rs);
;                     } else {
;                         const int i = (wc & 1) * 16 + fr;
;                         const float2 cs = r64[sq * 32 + i];
; #pragma unroll
;                         for (int bj = 0; bj < 2; ++bj) {
;                             const int head = ((bcol - 1024) >> 8) * 4 + bj * 2 + (wc >> 1);
;                             const float x1 = acc[ai][bj][m][0][j] * rs, x2 = acc[ai][bj][m][1][j] * rs;
;                             GAS bf16_t* p = (GAS bf16_t*)(qm + ((size_t)(b * 8 + head) * S + sq) * 192 + 128);
;                             p[i] = f2bf(x1 * cs.x - x2 * cs.y); p[32 + i] = f2bf(x2 * cs.x + x1 * cs.y);
;                         }
.LBB0_867:
	v_add_u32_e32 v20, 0xb1, v134
	v_and_b32_e32 v12, 0xffd, v20
	s_mov_b64 s[12:13], -1
	v_mov_b32_e32 v8, v182
	s_and_b64 vcc, exec, s[42:43]
	s_cbranch_vccnz .LBB0_869
	v_lshl_or_b32 v2, v12, 8, v1
	v_lshl_add_u64 v[20:21], s[50:51], 0, v[2:3]
	flat_load_dwordx2 v[20:21], v[20:21]
	v_lshlrev_b64 v[22:23], 12, v[132:133]
	v_mul_f32_e32 v4, v5, v8
	v_or_b32_e32 v16, v22, v12
	v_mov_b64_e32 v[24:25], s[48:49]
	v_mul_f32_e32 v2, v9, v8
	v_mad_u64_u32 v[26:27], s[12:13], v16, s69, v[24:25]
	v_mad_i32_i24 v27, v23, s69, v27
	v_mov_b32_e32 v137, v3
	v_lshl_add_u64 v[22:23], v[26:27], 0, v[136:137]
	s_waitcnt vmcnt(0) lgkmcnt(0)
	v_mul_f32_e32 v16, v4, v21
	v_fma_f32 v16, v2, v20, -v16
	v_mul_f32_e32 v2, v2, v21
	v_fmac_f32_e32 v2, v4, v20
	v_cvt_pk_bf16_f32 v16, v16, s0
	v_cvt_pk_bf16_f32 v2, v2, s0
	global_store_short v[22:23], v16, off offset:256
	global_store_short v[22:23], v2, off offset:320
	v_lshlrev_b64 v[22:23], 12, v[138:139]
	v_mul_f32_e32 v4, v17, v8
	v_or_b32_e32 v16, v22, v12
	v_mul_f32_e32 v2, v13, v8
	v_mad_u64_u32 v[24:25], s[12:13], v16, s69, v[24:25]
	v_mul_f32_e32 v16, v4, v21
	v_fma_f32 v16, v2, v20, -v16
	v_mul_f32_e32 v2, v2, v21
	v_mad_i32_i24 v25, v23, s69, v25
	v_fmac_f32_e32 v2, v4, v20
	v_cvt_pk_bf16_f32 v16, v16, s0
	v_lshl_add_u64 v[22:23], v[24:25], 0, v[136:137]
	v_cvt_pk_bf16_f32 v2, v2, s0
	s_mov_b64 s[12:13], 0
	global_store_short v[22:23], v16, off offset:256
	global_store_short v[22:23], v2, off offset:320

; #define GAS __attribute__((address_space(1)))
; __device__ __forceinline__ unsigned cvtpk(float lo, float hi) { return __builtin_bit_cast(unsigned, __builtin_convertvector(f32x2_cv{lo, hi}, bf16x2_cv)); }
; __device__ __forceinline__ bf16_t f2bf(float f) { return (bf16_t)(cvtpk(f, 0.f) & 0xffffu); }
;     __device__ __forceinline__ void operator()(const f32x4 (&acc)[2][2][4][2], int brow, int bcol, int wr, int wc, int fr, int fq) const {
;     ...
;                     const float rs = rstd_from_ssq(ssq, row);
;                     if (bcol < 1024) {
; #pragma unroll
;                         for (int bj = 0; bj < 2; ++bj)
;                             *(GAS unsigned*)(qm + ((size_t)(b * 8 + (bcol >> 7) + bj) * S + sq) * 192 + wc * 32 + 2 * fr) = cvtpk(acc[ai][bj][m][0][j] * rs, acc[ai][bj][m][1][j] * rs);
;                     } else {
;                         const int i = (wc & 1) * 16 + fr;
;                         const float2 cs = r64[sq * 32 + i];
; #pragma unroll
;                         for (int bj = 0; bj < 2; ++bj) {
;                             const int head = ((bcol - 1024) >> 8) * 4 + bj * 2 + (wc >> 1);
;                             const float x1 = acc[ai][bj][m][0][j] * rs, x2 = acc[ai][bj][m][1][j] * rs;
;                             GAS bf16_t* p = (GAS bf16_t*)(qm + ((size_t)(b * 8 + head) * S + sq) * 192 + 128);
;                             p[i] = f2bf(x1 * cs.x - x2 * cs.y); p[32 + i] = f2bf(x2 * cs.x + x1 * cs.y);
;                         }
.LBB0_871:
	v_add_u32_e32 v8, 0xb2, v134
	v_and_b32_e32 v5, 0xffe, v8
	s_mov_b64 s[12:13], -1
	v_mov_b32_e32 v4, v183
	s_and_b64 vcc, exec, s[42:43]
	s_cbranch_vccnz .LBB0_873
	v_lshl_or_b32 v2, v5, 8, v1
	v_lshl_add_u64 v[8:9], s[50:51], 0, v[2:3]
	flat_load_dwordx2 v[8:9], v[8:9]
	v_lshlrev_b64 v[12:13], 12, v[132:133]
	v_mul_f32_e32 v22, v6, v4
	v_or_b32_e32 v12, v12, v5
	v_mov_b64_e32 v[16:17], s[48:49]
	v_mul_f32_e32 v2, v10, v4
	v_mad_u64_u32 v[20:21], s[12:13], v12, s69, v[16:17]
	v_mad_i32_i24 v21, v13, s69, v21
	v_mov_b32_e32 v137, v3
	s_waitcnt vmcnt(0) lgkmcnt(0)
	v_mul_f32_e32 v12, v22, v9
	v_fma_f32 v12, v2, v8, -v12
	v_mul_f32_e32 v2, v2, v9
	v_fmac_f32_e32 v2, v22, v8
	v_cvt_pk_bf16_f32 v23, v12, s0
	v_lshl_add_u64 v[12:13], v[20:21], 0, v[136:137]
	v_cvt_pk_bf16_f32 v2, v2, s0
	global_store_short v[12:13], v23, off offset:256
	global_store_short v[12:13], v2, off offset:320
	v_lshlrev_b64 v[12:13], 12, v[138:139]
	v_mul_f32_e32 v20, v18, v4
	v_or_b32_e32 v12, v12, v5
	v_mul_f32_e32 v2, v14, v4
	v_mad_u64_u32 v[16:17], s[12:13], v12, s69, v[16:17]
	v_mul_f32_e32 v12, v20, v9
	v_fma_f32 v12, v2, v8, -v12
	v_mul_f32_e32 v2, v2, v9
	v_mad_i32_i24 v17, v13, s69, v17
	v_fmac_f32_e32 v2, v20, v8
	v_cvt_pk_bf16_f32 v21, v12, s0
	v_lshl_add_u64 v[12:13], v[16:17], 0, v[136:137]
	v_cvt_pk_bf16_f32 v2, v2, s0
	s_mov_b64 s[12:13], 0
	global_store_short v[12:13], v21, off offset:256
	global_store_short v[12:13], v2, off offset:320

; #define GAS __attribute__((address_space(1)))
; __device__ __forceinline__ unsigned cvtpk(float lo, float hi) { return __builtin_bit_cast(unsigned, __builtin_convertvector(f32x2_cv{lo, hi}, bf16x2_cv)); }
; __device__ __forceinline__ bf16_t f2bf(float f) { return (bf16_t)(cvtpk(f, 0.f) & 0xffffu); }
;     __device__ __forceinline__ void operator()(const f32x4 (&acc)[2][2][4][2], int brow, int bcol, int wr, int wc, int fr, int fq) const {
;     ...
;                     const float rs = rstd_from_ssq(ssq, row);
;                     if (bcol < 1024) {
; #pragma unroll
;                         for (int bj = 0; bj < 2; ++bj)
;                             *(GAS unsigned*)(qm + ((size_t)(b * 8 + (bcol >> 7) + bj) * S + sq) * 192 + wc * 32 + 2 * fr) = cvtpk(acc[ai][bj][m][0][j] * rs, acc[ai][bj][m][1][j] * rs);
;                     } else {
;                         const int i = (wc & 1) * 16 + fr;
;                         const float2 cs = r64[sq * 32 + i];
; #pragma unroll
;                         for (int bj = 0; bj < 2; ++bj) {
;                             const int head = ((bcol - 1024) >> 8) * 4 + bj * 2 + (wc >> 1);
;                             const float x1 = acc[ai][bj][m][0][j] * rs, x2 = acc[ai][bj][m][1][j] * rs;
;                             GAS bf16_t* p = (GAS bf16_t*)(qm + ((size_t)(b * 8 + head) * S + sq) * 192 + 128);
;                             p[i] = f2bf(x1 * cs.x - x2 * cs.y); p[32 + i] = f2bf(x2 * cs.x + x1 * cs.y);
;                         }
.LBB0_875:
	v_add_u32_e32 v8, 0xb3, v134
	v_and_b32_e32 v5, 0xfff, v8
	s_mov_b64 s[12:13], -1
	v_mov_b32_e32 v4, v184
	s_and_b64 vcc, exec, s[42:43]
	s_cbranch_vccnz .LBB0_877
	v_lshl_or_b32 v2, v5, 8, v1
	v_lshl_add_u64 v[8:9], s[50:51], 0, v[2:3]
	flat_load_dwordx2 v[8:9], v[8:9]
	v_lshlrev_b64 v[12:13], 12, v[132:133]
	v_mul_f32_e32 v2, v7, v4
	v_or_b32_e32 v6, v12, v5
	v_mov_b64_e32 v[16:17], s[48:49]
	v_mul_f32_e32 v1, v11, v4
	v_mad_u64_u32 v[20:21], s[12:13], v6, s69, v[16:17]
	v_mad_i32_i24 v21, v13, s69, v21
	v_mov_b32_e32 v137, v3
	v_lshl_add_u64 v[12:13], v[20:21], 0, v[136:137]
	s_waitcnt vmcnt(0) lgkmcnt(0)
	v_mul_f32_e32 v6, v2, v9
	v_fma_f32 v6, v1, v8, -v6
	v_mul_f32_e32 v1, v1, v9
	v_fmac_f32_e32 v1, v2, v8
	v_cvt_pk_bf16_f32 v6, v6, s0
	v_cvt_pk_bf16_f32 v1, v1, s0
	global_store_short v[12:13], v6, off offset:256
	global_store_short v[12:13], v1, off offset:320
	v_lshlrev_b64 v[12:13], 12, v[138:139]
	v_mul_f32_e32 v2, v19, v4
	v_or_b32_e32 v6, v12, v5
	v_mul_f32_e32 v1, v15, v4
	v_mad_u64_u32 v[16:17], s[12:13], v6, s69, v[16:17]
	v_mul_f32_e32 v6, v2, v9
	v_fma_f32 v6, v1, v8, -v6
	v_mul_f32_e32 v1, v1, v9
	v_mad_i32_i24 v17, v13, s69, v17
	v_fmac_f32_e32 v1, v2, v8
	v_cvt_pk_bf16_f32 v6, v6, s0
	v_lshl_add_u64 v[12:13], v[16:17], 0, v[136:137]
	v_cvt_pk_bf16_f32 v1, v1, s0
	global_store_short v[12:13], v6, off offset:256
	global_store_short v[12:13], v1, off offset:320
	s_cbranch_execnz .LBB0_744
	s_branch .LBB0_878
